# hand-written S2 chunk scan (16 chunks in flight) on top of the hand-written phase 0
# speedup vs baseline: 1.0004x; 1.0004x over previous
; __device__ __forceinline__ unsigned pk2(float lo, float hi) { const f32x2_t_ v = {lo, hi}; return __builtin_bit_cast(unsigned, __builtin_convertvector(v, bf16x2_t_)); }
; __device__ __forceinline__ void ssd_s2_phase(Frame& F, bf16* states, const float* decay) {
;     for (int it = blockIdx.x * 512 + F.tid; it < SSD_NH * 64 * 16; it += F.G * 512) {
;         const int h = it >> 10; float H[8];
; #pragma unroll
;         for (int j = 0; j < 8; ++j) H[j] = 0.f;
;         v4u* sp = (v4u*)(states + (size_t)it * 8);
; #pragma unroll 8
;         for (int c = 0; c < 64; ++c) { const v4u q = sp[(size_t)c * (128 * 64 * 16)]; const float dec = decay[(c * 8 + (h >> 4)) * 32 + (h & 15)];
;             v4u o; o.x = pk2(H[0], H[1]); o.y = pk2(H[2], H[3]); o.z = pk2(H[4], H[5]); o.w = pk2(H[6], H[7]);
;             sp[(size_t)c * (128 * 64 * 16)] = o;
;             H[0] = H[0] * dec + bflo(q.x); H[1] = H[1] * dec + bfhi(q.x); H[2] = H[2] * dec + bflo(q.y); H[3] = H[3] * dec + bfhi(q.y);
;             H[4] = H[4] * dec + bflo(q.z); H[5] = H[5] * dec + bfhi(q.z); H[6] = H[6] * dec + bflo(q.w); H[7] = H[7] * dec + bfhi(q.w); }
.LBB0_487:
	s_load_dwordx2 s[2:3], s[74:75], 0x100
	s_waitcnt lgkmcnt(0)
	s_cmp_lt_i32 s2, 5
	s_cselect_b64 s[2:3], -1, 0
	s_and_b64 s[2:3], s[2:3], s[0:1]
	s_andn2_b64 vcc, exec, s[2:3]
	s_cbranch_vccnz .LBB0_494
	s_load_dword s99, s[74:75], 0x108
	s_lshl_b32 s98, s93, 9
	s_add_i32 s98, s98, s94
	v_lshlrev_b32_e32 v1, 4, v186
	v_mov_b32_e32 v2, 0
	s_waitcnt lgkmcnt(0)
	s_lshl_b32 s99, s99, 9
.Ls2a_outer:
	s_cmp_lt_u32 s98, 0x20000
	s_cbranch_scc0 .Ls2a_done
	s_lshl_b32 s0, s98, 4
	s_add_u32 s0, s0, 0x4c300000
	s_add_u32 s70, s78, s0
	s_addc_u32 s71, s79, 0
	s_mov_b64 s[72:73], s[70:71]
	s_lshr_b32 s0, s98, 10
	s_lshr_b32 s1, s0, 4
	s_and_b32 s0, s0, 15
	s_lshl_b32 s1, s1, 7
	s_lshl_b32 s0, s0, 2
	s_add_i32 s0, s0, s1
	s_add_u32 s0, s0, 0x6a780000
	s_add_u32 s100, s78, s0
	s_addc_u32 s101, s79, 0
	v_mov_b32_e32 v4, 0
	v_mov_b32_e32 v5, 0
	v_mov_b32_e32 v6, 0
	v_mov_b32_e32 v7, 0
	v_mov_b32_e32 v8, 0
	v_mov_b32_e32 v9, 0
	v_mov_b32_e32 v10, 0
	v_mov_b32_e32 v11, 0
	global_load_dwordx4 v[30:33], v1, s[70:71]
	s_add_u32 s70, s70, 0x200000
	s_addc_u32 s71, s71, 0
	global_load_dword v94, v2, s[100:101]
	s_add_u32 s100, s100, 0x400
	s_addc_u32 s101, s101, 0
	global_load_dwordx4 v[34:37], v1, s[70:71]
	s_add_u32 s70, s70, 0x200000
	s_addc_u32 s71, s71, 0
	global_load_dword v95, v2, s[100:101]
	s_add_u32 s100, s100, 0x400
	s_addc_u32 s101, s101, 0
	global_load_dwordx4 v[38:41], v1, s[70:71]
	s_add_u32 s70, s70, 0x200000
	s_addc_u32 s71, s71, 0
	global_load_dword v96, v2, s[100:101]
	s_add_u32 s100, s100, 0x400
	s_addc_u32 s101, s101, 0
	global_load_dwordx4 v[42:45], v1, s[70:71]
	s_add_u32 s70, s70, 0x200000
	s_addc_u32 s71, s71, 0
	global_load_dword v97, v2, s[100:101]
	s_add_u32 s100, s100, 0x400
	s_addc_u32 s101, s101, 0
	global_load_dwordx4 v[46:49], v1, s[70:71]
	s_add_u32 s70, s70, 0x200000
	s_addc_u32 s71, s71, 0
	global_load_dword v98, v2, s[100:101]
	s_add_u32 s100, s100, 0x400
	s_addc_u32 s101, s101, 0
	global_load_dwordx4 v[50:53], v1, s[70:71]
	s_add_u32 s70, s70, 0x200000
	s_addc_u32 s71, s71, 0
	global_load_dword v99, v2, s[100:101]
	s_add_u32 s100, s100, 0x400
	s_addc_u32 s101, s101, 0
	global_load_dwordx4 v[54:57], v1, s[70:71]
	s_add_u32 s70, s70, 0x200000
	s_addc_u32 s71, s71, 0
	global_load_dword v100, v2, s[100:101]
	s_add_u32 s100, s100, 0x400
	s_addc_u32 s101, s101, 0
	global_load_dwordx4 v[58:61], v1, s[70:71]
	s_add_u32 s70, s70, 0x200000
	s_addc_u32 s71, s71, 0
	global_load_dword v101, v2, s[100:101]
	s_add_u32 s100, s100, 0x400
	s_addc_u32 s101, s101, 0
	global_load_dwordx4 v[62:65], v1, s[70:71]
	s_add_u32 s70, s70, 0x200000
	s_addc_u32 s71, s71, 0
	global_load_dword v102, v2, s[100:101]
	s_add_u32 s100, s100, 0x400
	s_addc_u32 s101, s101, 0
	global_load_dwordx4 v[66:69], v1, s[70:71]
	s_add_u32 s70, s70, 0x200000
	s_addc_u32 s71, s71, 0
	global_load_dword v103, v2, s[100:101]
	s_add_u32 s100, s100, 0x400
	s_addc_u32 s101, s101, 0
	global_load_dwordx4 v[70:73], v1, s[70:71]
	s_add_u32 s70, s70, 0x200000
	s_addc_u32 s71, s71, 0
	global_load_dword v104, v2, s[100:101]
	s_add_u32 s100, s100, 0x400
	s_addc_u32 s101, s101, 0
	global_load_dwordx4 v[74:77], v1, s[70:71]
	s_add_u32 s70, s70, 0x200000
	s_addc_u32 s71, s71, 0
	global_load_dword v105, v2, s[100:101]
	s_add_u32 s100, s100, 0x400
	s_addc_u32 s101, s101, 0
	global_load_dwordx4 v[78:81], v1, s[70:71]
	s_add_u32 s70, s70, 0x200000
	s_addc_u32 s71, s71, 0
	global_load_dword v106, v2, s[100:101]
	s_add_u32 s100, s100, 0x400
	s_addc_u32 s101, s101, 0
	global_load_dwordx4 v[82:85], v1, s[70:71]
	s_add_u32 s70, s70, 0x200000
	s_addc_u32 s71, s71, 0
	global_load_dword v107, v2, s[100:101]
	s_add_u32 s100, s100, 0x400
	s_addc_u32 s101, s101, 0
	global_load_dwordx4 v[86:89], v1, s[70:71]
	s_add_u32 s70, s70, 0x200000
	s_addc_u32 s71, s71, 0
	global_load_dword v108, v2, s[100:101]
	s_add_u32 s100, s100, 0x400
	s_addc_u32 s101, s101, 0
	global_load_dwordx4 v[90:93], v1, s[70:71]
	s_add_u32 s70, s70, 0x200000
	s_addc_u32 s71, s71, 0
	global_load_dword v109, v2, s[100:101]
	s_add_u32 s100, s100, 0x400
	s_addc_u32 s101, s101, 0
	s_waitcnt vmcnt(30)
	v_cvt_pk_bf16_f32 v12, v4, v5
	v_cvt_pk_bf16_f32 v13, v6, v7
	v_cvt_pk_bf16_f32 v14, v8, v9
	v_cvt_pk_bf16_f32 v15, v10, v11
	global_store_dwordx4 v1, v[12:15], s[72:73]
	s_add_u32 s72, s72, 0x200000
	s_addc_u32 s73, s73, 0
	v_lshlrev_b32_e32 v20, 16, v30
	v_and_b32_e32 v21, 0xffff0000, v30
	v_lshlrev_b32_e32 v22, 16, v31
	v_and_b32_e32 v23, 0xffff0000, v31
	v_lshlrev_b32_e32 v24, 16, v32
	v_and_b32_e32 v25, 0xffff0000, v32
	v_lshlrev_b32_e32 v26, 16, v33
	v_and_b32_e32 v27, 0xffff0000, v33
	v_fma_f32 v4, v4, v94, v20
	v_fma_f32 v5, v5, v94, v21
	v_fma_f32 v6, v6, v94, v22
	v_fma_f32 v7, v7, v94, v23
	v_fma_f32 v8, v8, v94, v24
	v_fma_f32 v9, v9, v94, v25
	v_fma_f32 v10, v10, v94, v26
	v_fma_f32 v11, v11, v94, v27
	global_load_dwordx4 v[30:33], v1, s[70:71]
	s_add_u32 s70, s70, 0x200000
	s_addc_u32 s71, s71, 0
	global_load_dword v94, v2, s[100:101]
	s_add_u32 s100, s100, 0x400
	s_addc_u32 s101, s101, 0
	s_waitcnt vmcnt(31)
	v_cvt_pk_bf16_f32 v16, v4, v5
	v_cvt_pk_bf16_f32 v17, v6, v7
	v_cvt_pk_bf16_f32 v18, v8, v9
	v_cvt_pk_bf16_f32 v19, v10, v11
	global_store_dwordx4 v1, v[16:19], s[72:73]
	s_add_u32 s72, s72, 0x200000
	s_addc_u32 s73, s73, 0
	v_lshlrev_b32_e32 v20, 16, v34
	v_and_b32_e32 v21, 0xffff0000, v34
	v_lshlrev_b32_e32 v22, 16, v35
	v_and_b32_e32 v23, 0xffff0000, v35
	v_lshlrev_b32_e32 v24, 16, v36
	v_and_b32_e32 v25, 0xffff0000, v36
	v_lshlrev_b32_e32 v26, 16, v37
	v_and_b32_e32 v27, 0xffff0000, v37
	v_fma_f32 v4, v4, v95, v20
	v_fma_f32 v5, v5, v95, v21
	v_fma_f32 v6, v6, v95, v22
	v_fma_f32 v7, v7, v95, v23
	v_fma_f32 v8, v8, v95, v24
	v_fma_f32 v9, v9, v95, v25
	v_fma_f32 v10, v10, v95, v26
	v_fma_f32 v11, v11, v95, v27
	global_load_dwordx4 v[34:37], v1, s[70:71]
	s_add_u32 s70, s70, 0x200000
	s_addc_u32 s71, s71, 0
	global_load_dword v95, v2, s[100:101]
	s_add_u32 s100, s100, 0x400
	s_addc_u32 s101, s101, 0
	s_waitcnt vmcnt(32)
; __device__ __forceinline__ unsigned pk2(float lo, float hi) { const f32x2_t_ v = {lo, hi}; return __builtin_bit_cast(unsigned, __builtin_convertvector(v, bf16x2_t_)); }
; __device__ __forceinline__ void ssd_s2_phase(Frame& F, bf16* states, const float* decay) {
;     ...
;         for (int c = 0; c < 64; ++c) { const v4u q = sp[(size_t)c * (128 * 64 * 16)]; const float dec = decay[(c * 8 + (h >> 4)) * 32 + (h & 15)];
;             v4u o; o.x = pk2(H[0], H[1]); o.y = pk2(H[2], H[3]); o.z = pk2(H[4], H[5]); o.w = pk2(H[6], H[7]);
;             sp[(size_t)c * (128 * 64 * 16)] = o;
;             H[0] = H[0] * dec + bflo(q.x); H[1] = H[1] * dec + bfhi(q.x); H[2] = H[2] * dec + bflo(q.y); H[3] = H[3] * dec + bfhi(q.y);
;             H[4] = H[4] * dec + bflo(q.z); H[5] = H[5] * dec + bfhi(q.z); H[6] = H[6] * dec + bflo(q.w); H[7] = H[7] * dec + bfhi(q.w); }
	v_cvt_pk_bf16_f32 v12, v4, v5
	v_cvt_pk_bf16_f32 v13, v6, v7
	v_cvt_pk_bf16_f32 v14, v8, v9
	v_cvt_pk_bf16_f32 v15, v10, v11
	global_store_dwordx4 v1, v[12:15], s[72:73]
	s_add_u32 s72, s72, 0x200000
	s_addc_u32 s73, s73, 0
	v_lshlrev_b32_e32 v20, 16, v38
	v_and_b32_e32 v21, 0xffff0000, v38
	v_lshlrev_b32_e32 v22, 16, v39
	v_and_b32_e32 v23, 0xffff0000, v39
	v_lshlrev_b32_e32 v24, 16, v40
	v_and_b32_e32 v25, 0xffff0000, v40
	v_lshlrev_b32_e32 v26, 16, v41
	v_and_b32_e32 v27, 0xffff0000, v41
	v_fma_f32 v4, v4, v96, v20
	v_fma_f32 v5, v5, v96, v21
	v_fma_f32 v6, v6, v96, v22
	v_fma_f32 v7, v7, v96, v23
	v_fma_f32 v8, v8, v96, v24
	v_fma_f32 v9, v9, v96, v25
	v_fma_f32 v10, v10, v96, v26
	v_fma_f32 v11, v11, v96, v27
	global_load_dwordx4 v[38:41], v1, s[70:71]
	s_add_u32 s70, s70, 0x200000
	s_addc_u32 s71, s71, 0
	global_load_dword v96, v2, s[100:101]
	s_add_u32 s100, s100, 0x400
	s_addc_u32 s101, s101, 0
	s_waitcnt vmcnt(33)
	v_cvt_pk_bf16_f32 v16, v4, v5
	v_cvt_pk_bf16_f32 v17, v6, v7
	v_cvt_pk_bf16_f32 v18, v8, v9
	v_cvt_pk_bf16_f32 v19, v10, v11
	global_store_dwordx4 v1, v[16:19], s[72:73]
	s_add_u32 s72, s72, 0x200000
	s_addc_u32 s73, s73, 0
	v_lshlrev_b32_e32 v20, 16, v42
	v_and_b32_e32 v21, 0xffff0000, v42
	v_lshlrev_b32_e32 v22, 16, v43
	v_and_b32_e32 v23, 0xffff0000, v43
	v_lshlrev_b32_e32 v24, 16, v44
	v_and_b32_e32 v25, 0xffff0000, v44
	v_lshlrev_b32_e32 v26, 16, v45
	v_and_b32_e32 v27, 0xffff0000, v45
	v_fma_f32 v4, v4, v97, v20
	v_fma_f32 v5, v5, v97, v21
	v_fma_f32 v6, v6, v97, v22
	v_fma_f32 v7, v7, v97, v23
	v_fma_f32 v8, v8, v97, v24
	v_fma_f32 v9, v9, v97, v25
	v_fma_f32 v10, v10, v97, v26
	v_fma_f32 v11, v11, v97, v27
	global_load_dwordx4 v[42:45], v1, s[70:71]
	s_add_u32 s70, s70, 0x200000
	s_addc_u32 s71, s71, 0
	global_load_dword v97, v2, s[100:101]
	s_add_u32 s100, s100, 0x400
	s_addc_u32 s101, s101, 0
	s_waitcnt vmcnt(34)
	v_cvt_pk_bf16_f32 v12, v4, v5
	v_cvt_pk_bf16_f32 v13, v6, v7
	v_cvt_pk_bf16_f32 v14, v8, v9
	v_cvt_pk_bf16_f32 v15, v10, v11
	global_store_dwordx4 v1, v[12:15], s[72:73]
	s_add_u32 s72, s72, 0x200000
	s_addc_u32 s73, s73, 0
	v_lshlrev_b32_e32 v20, 16, v46
	v_and_b32_e32 v21, 0xffff0000, v46
	v_lshlrev_b32_e32 v22, 16, v47
	v_and_b32_e32 v23, 0xffff0000, v47
	v_lshlrev_b32_e32 v24, 16, v48
	v_and_b32_e32 v25, 0xffff0000, v48
	v_lshlrev_b32_e32 v26, 16, v49
	v_and_b32_e32 v27, 0xffff0000, v49
	v_fma_f32 v4, v4, v98, v20
	v_fma_f32 v5, v5, v98, v21
	v_fma_f32 v6, v6, v98, v22
	v_fma_f32 v7, v7, v98, v23
	v_fma_f32 v8, v8, v98, v24
	v_fma_f32 v9, v9, v98, v25
	v_fma_f32 v10, v10, v98, v26
	v_fma_f32 v11, v11, v98, v27
	global_load_dwordx4 v[46:49], v1, s[70:71]
	s_add_u32 s70, s70, 0x200000
	s_addc_u32 s71, s71, 0
	global_load_dword v98, v2, s[100:101]
	s_add_u32 s100, s100, 0x400
	s_addc_u32 s101, s101, 0
	s_waitcnt vmcnt(35)
	v_cvt_pk_bf16_f32 v16, v4, v5
	v_cvt_pk_bf16_f32 v17, v6, v7
	v_cvt_pk_bf16_f32 v18, v8, v9
	v_cvt_pk_bf16_f32 v19, v10, v11
	global_store_dwordx4 v1, v[16:19], s[72:73]
	s_add_u32 s72, s72, 0x200000
	s_addc_u32 s73, s73, 0
	v_lshlrev_b32_e32 v20, 16, v50
	v_and_b32_e32 v21, 0xffff0000, v50
	v_lshlrev_b32_e32 v22, 16, v51
	v_and_b32_e32 v23, 0xffff0000, v51
	v_lshlrev_b32_e32 v24, 16, v52
	v_and_b32_e32 v25, 0xffff0000, v52
	v_lshlrev_b32_e32 v26, 16, v53
	v_and_b32_e32 v27, 0xffff0000, v53
	v_fma_f32 v4, v4, v99, v20
	v_fma_f32 v5, v5, v99, v21
	v_fma_f32 v6, v6, v99, v22
	v_fma_f32 v7, v7, v99, v23
	v_fma_f32 v8, v8, v99, v24
	v_fma_f32 v9, v9, v99, v25
	v_fma_f32 v10, v10, v99, v26
	v_fma_f32 v11, v11, v99, v27
	global_load_dwordx4 v[50:53], v1, s[70:71]
	s_add_u32 s70, s70, 0x200000
	s_addc_u32 s71, s71, 0
	global_load_dword v99, v2, s[100:101]
	s_add_u32 s100, s100, 0x400
	s_addc_u32 s101, s101, 0
	s_waitcnt vmcnt(36)
	v_cvt_pk_bf16_f32 v12, v4, v5
	v_cvt_pk_bf16_f32 v13, v6, v7
	v_cvt_pk_bf16_f32 v14, v8, v9
	v_cvt_pk_bf16_f32 v15, v10, v11
	global_store_dwordx4 v1, v[12:15], s[72:73]
	s_add_u32 s72, s72, 0x200000
	s_addc_u32 s73, s73, 0
	v_lshlrev_b32_e32 v20, 16, v54
	v_and_b32_e32 v21, 0xffff0000, v54
	v_lshlrev_b32_e32 v22, 16, v55
	v_and_b32_e32 v23, 0xffff0000, v55
	v_lshlrev_b32_e32 v24, 16, v56
	v_and_b32_e32 v25, 0xffff0000, v56
	v_lshlrev_b32_e32 v26, 16, v57
	v_and_b32_e32 v27, 0xffff0000, v57
	v_fma_f32 v4, v4, v100, v20
	v_fma_f32 v5, v5, v100, v21
	v_fma_f32 v6, v6, v100, v22
	v_fma_f32 v7, v7, v100, v23
	v_fma_f32 v8, v8, v100, v24
	v_fma_f32 v9, v9, v100, v25
	v_fma_f32 v10, v10, v100, v26
	v_fma_f32 v11, v11, v100, v27
	global_load_dwordx4 v[54:57], v1, s[70:71]
	s_add_u32 s70, s70, 0x200000
	s_addc_u32 s71, s71, 0
	global_load_dword v100, v2, s[100:101]
	s_add_u32 s100, s100, 0x400
	s_addc_u32 s101, s101, 0
	s_waitcnt vmcnt(37)
	v_cvt_pk_bf16_f32 v16, v4, v5
	v_cvt_pk_bf16_f32 v17, v6, v7
	v_cvt_pk_bf16_f32 v18, v8, v9
	v_cvt_pk_bf16_f32 v19, v10, v11
	global_store_dwordx4 v1, v[16:19], s[72:73]
	s_add_u32 s72, s72, 0x200000
	s_addc_u32 s73, s73, 0
	v_lshlrev_b32_e32 v20, 16, v58
	v_and_b32_e32 v21, 0xffff0000, v58
	v_lshlrev_b32_e32 v22, 16, v59
	v_and_b32_e32 v23, 0xffff0000, v59
	v_lshlrev_b32_e32 v24, 16, v60
	v_and_b32_e32 v25, 0xffff0000, v60
	v_lshlrev_b32_e32 v26, 16, v61
	v_and_b32_e32 v27, 0xffff0000, v61
	v_fma_f32 v4, v4, v101, v20
	v_fma_f32 v5, v5, v101, v21
	v_fma_f32 v6, v6, v101, v22
	v_fma_f32 v7, v7, v101, v23
	v_fma_f32 v8, v8, v101, v24
	v_fma_f32 v9, v9, v101, v25
	v_fma_f32 v10, v10, v101, v26
	v_fma_f32 v11, v11, v101, v27
	global_load_dwordx4 v[58:61], v1, s[70:71]
	s_add_u32 s70, s70, 0x200000
	s_addc_u32 s71, s71, 0
	global_load_dword v101, v2, s[100:101]
	s_add_u32 s100, s100, 0x400
	s_addc_u32 s101, s101, 0
	s_waitcnt vmcnt(38)
; __device__ __forceinline__ unsigned pk2(float lo, float hi) { const f32x2_t_ v = {lo, hi}; return __builtin_bit_cast(unsigned, __builtin_convertvector(v, bf16x2_t_)); }
; __device__ __forceinline__ void ssd_s2_phase(Frame& F, bf16* states, const float* decay) {
;     ...
;         for (int c = 0; c < 64; ++c) { const v4u q = sp[(size_t)c * (128 * 64 * 16)]; const float dec = decay[(c * 8 + (h >> 4)) * 32 + (h & 15)];
;             v4u o; o.x = pk2(H[0], H[1]); o.y = pk2(H[2], H[3]); o.z = pk2(H[4], H[5]); o.w = pk2(H[6], H[7]);
;             sp[(size_t)c * (128 * 64 * 16)] = o;
;             H[0] = H[0] * dec + bflo(q.x); H[1] = H[1] * dec + bfhi(q.x); H[2] = H[2] * dec + bflo(q.y); H[3] = H[3] * dec + bfhi(q.y);
;             H[4] = H[4] * dec + bflo(q.z); H[5] = H[5] * dec + bfhi(q.z); H[6] = H[6] * dec + bflo(q.w); H[7] = H[7] * dec + bfhi(q.w); }
	v_cvt_pk_bf16_f32 v12, v4, v5
	v_cvt_pk_bf16_f32 v13, v6, v7
	v_cvt_pk_bf16_f32 v14, v8, v9
	v_cvt_pk_bf16_f32 v15, v10, v11
	global_store_dwordx4 v1, v[12:15], s[72:73]
	s_add_u32 s72, s72, 0x200000
	s_addc_u32 s73, s73, 0
	v_lshlrev_b32_e32 v20, 16, v62
	v_and_b32_e32 v21, 0xffff0000, v62
	v_lshlrev_b32_e32 v22, 16, v63
	v_and_b32_e32 v23, 0xffff0000, v63
	v_lshlrev_b32_e32 v24, 16, v64
	v_and_b32_e32 v25, 0xffff0000, v64
	v_lshlrev_b32_e32 v26, 16, v65
	v_and_b32_e32 v27, 0xffff0000, v65
	v_fma_f32 v4, v4, v102, v20
	v_fma_f32 v5, v5, v102, v21
	v_fma_f32 v6, v6, v102, v22
	v_fma_f32 v7, v7, v102, v23
	v_fma_f32 v8, v8, v102, v24
	v_fma_f32 v9, v9, v102, v25
	v_fma_f32 v10, v10, v102, v26
	v_fma_f32 v11, v11, v102, v27
	global_load_dwordx4 v[62:65], v1, s[70:71]
	s_add_u32 s70, s70, 0x200000
	s_addc_u32 s71, s71, 0
	global_load_dword v102, v2, s[100:101]
	s_add_u32 s100, s100, 0x400
	s_addc_u32 s101, s101, 0
	s_waitcnt vmcnt(39)
	v_cvt_pk_bf16_f32 v16, v4, v5
	v_cvt_pk_bf16_f32 v17, v6, v7
	v_cvt_pk_bf16_f32 v18, v8, v9
	v_cvt_pk_bf16_f32 v19, v10, v11
	global_store_dwordx4 v1, v[16:19], s[72:73]
	s_add_u32 s72, s72, 0x200000
	s_addc_u32 s73, s73, 0
	v_lshlrev_b32_e32 v20, 16, v66
	v_and_b32_e32 v21, 0xffff0000, v66
	v_lshlrev_b32_e32 v22, 16, v67
	v_and_b32_e32 v23, 0xffff0000, v67
	v_lshlrev_b32_e32 v24, 16, v68
	v_and_b32_e32 v25, 0xffff0000, v68
	v_lshlrev_b32_e32 v26, 16, v69
	v_and_b32_e32 v27, 0xffff0000, v69
	v_fma_f32 v4, v4, v103, v20
	v_fma_f32 v5, v5, v103, v21
	v_fma_f32 v6, v6, v103, v22
	v_fma_f32 v7, v7, v103, v23
	v_fma_f32 v8, v8, v103, v24
	v_fma_f32 v9, v9, v103, v25
	v_fma_f32 v10, v10, v103, v26
	v_fma_f32 v11, v11, v103, v27
	global_load_dwordx4 v[66:69], v1, s[70:71]
	s_add_u32 s70, s70, 0x200000
	s_addc_u32 s71, s71, 0
	global_load_dword v103, v2, s[100:101]
	s_add_u32 s100, s100, 0x400
	s_addc_u32 s101, s101, 0
	s_waitcnt vmcnt(40)
	v_cvt_pk_bf16_f32 v12, v4, v5
	v_cvt_pk_bf16_f32 v13, v6, v7
	v_cvt_pk_bf16_f32 v14, v8, v9
	v_cvt_pk_bf16_f32 v15, v10, v11
	global_store_dwordx4 v1, v[12:15], s[72:73]
	s_add_u32 s72, s72, 0x200000
	s_addc_u32 s73, s73, 0
	v_lshlrev_b32_e32 v20, 16, v70
	v_and_b32_e32 v21, 0xffff0000, v70
	v_lshlrev_b32_e32 v22, 16, v71
	v_and_b32_e32 v23, 0xffff0000, v71
	v_lshlrev_b32_e32 v24, 16, v72
	v_and_b32_e32 v25, 0xffff0000, v72
	v_lshlrev_b32_e32 v26, 16, v73
	v_and_b32_e32 v27, 0xffff0000, v73
	v_fma_f32 v4, v4, v104, v20
	v_fma_f32 v5, v5, v104, v21
	v_fma_f32 v6, v6, v104, v22
	v_fma_f32 v7, v7, v104, v23
	v_fma_f32 v8, v8, v104, v24
	v_fma_f32 v9, v9, v104, v25
	v_fma_f32 v10, v10, v104, v26
	v_fma_f32 v11, v11, v104, v27
	global_load_dwordx4 v[70:73], v1, s[70:71]
	s_add_u32 s70, s70, 0x200000
	s_addc_u32 s71, s71, 0
	global_load_dword v104, v2, s[100:101]
	s_add_u32 s100, s100, 0x400
	s_addc_u32 s101, s101, 0
	s_waitcnt vmcnt(41)
	v_cvt_pk_bf16_f32 v16, v4, v5
	v_cvt_pk_bf16_f32 v17, v6, v7
	v_cvt_pk_bf16_f32 v18, v8, v9
	v_cvt_pk_bf16_f32 v19, v10, v11
	global_store_dwordx4 v1, v[16:19], s[72:73]
	s_add_u32 s72, s72, 0x200000
	s_addc_u32 s73, s73, 0
	v_lshlrev_b32_e32 v20, 16, v74
	v_and_b32_e32 v21, 0xffff0000, v74
	v_lshlrev_b32_e32 v22, 16, v75
	v_and_b32_e32 v23, 0xffff0000, v75
	v_lshlrev_b32_e32 v24, 16, v76
	v_and_b32_e32 v25, 0xffff0000, v76
	v_lshlrev_b32_e32 v26, 16, v77
	v_and_b32_e32 v27, 0xffff0000, v77
	v_fma_f32 v4, v4, v105, v20
	v_fma_f32 v5, v5, v105, v21
	v_fma_f32 v6, v6, v105, v22
	v_fma_f32 v7, v7, v105, v23
	v_fma_f32 v8, v8, v105, v24
	v_fma_f32 v9, v9, v105, v25
	v_fma_f32 v10, v10, v105, v26
	v_fma_f32 v11, v11, v105, v27
	global_load_dwordx4 v[74:77], v1, s[70:71]
	s_add_u32 s70, s70, 0x200000
	s_addc_u32 s71, s71, 0
	global_load_dword v105, v2, s[100:101]
	s_add_u32 s100, s100, 0x400
	s_addc_u32 s101, s101, 0
	s_waitcnt vmcnt(42)
	v_cvt_pk_bf16_f32 v12, v4, v5
	v_cvt_pk_bf16_f32 v13, v6, v7
	v_cvt_pk_bf16_f32 v14, v8, v9
	v_cvt_pk_bf16_f32 v15, v10, v11
	global_store_dwordx4 v1, v[12:15], s[72:73]
	s_add_u32 s72, s72, 0x200000
	s_addc_u32 s73, s73, 0
	v_lshlrev_b32_e32 v20, 16, v78
	v_and_b32_e32 v21, 0xffff0000, v78
	v_lshlrev_b32_e32 v22, 16, v79
	v_and_b32_e32 v23, 0xffff0000, v79
	v_lshlrev_b32_e32 v24, 16, v80
	v_and_b32_e32 v25, 0xffff0000, v80
	v_lshlrev_b32_e32 v26, 16, v81
	v_and_b32_e32 v27, 0xffff0000, v81
	v_fma_f32 v4, v4, v106, v20
	v_fma_f32 v5, v5, v106, v21
	v_fma_f32 v6, v6, v106, v22
	v_fma_f32 v7, v7, v106, v23
	v_fma_f32 v8, v8, v106, v24
	v_fma_f32 v9, v9, v106, v25
	v_fma_f32 v10, v10, v106, v26
	v_fma_f32 v11, v11, v106, v27
	global_load_dwordx4 v[78:81], v1, s[70:71]
	s_add_u32 s70, s70, 0x200000
	s_addc_u32 s71, s71, 0
	global_load_dword v106, v2, s[100:101]
	s_add_u32 s100, s100, 0x400
	s_addc_u32 s101, s101, 0
	s_waitcnt vmcnt(43)
	v_cvt_pk_bf16_f32 v16, v4, v5
	v_cvt_pk_bf16_f32 v17, v6, v7
	v_cvt_pk_bf16_f32 v18, v8, v9
	v_cvt_pk_bf16_f32 v19, v10, v11
	global_store_dwordx4 v1, v[16:19], s[72:73]
	s_add_u32 s72, s72, 0x200000
	s_addc_u32 s73, s73, 0
	v_lshlrev_b32_e32 v20, 16, v82
	v_and_b32_e32 v21, 0xffff0000, v82
	v_lshlrev_b32_e32 v22, 16, v83
	v_and_b32_e32 v23, 0xffff0000, v83
	v_lshlrev_b32_e32 v24, 16, v84
	v_and_b32_e32 v25, 0xffff0000, v84
	v_lshlrev_b32_e32 v26, 16, v85
	v_and_b32_e32 v27, 0xffff0000, v85
	v_fma_f32 v4, v4, v107, v20
	v_fma_f32 v5, v5, v107, v21
	v_fma_f32 v6, v6, v107, v22
	v_fma_f32 v7, v7, v107, v23
	v_fma_f32 v8, v8, v107, v24
	v_fma_f32 v9, v9, v107, v25
	v_fma_f32 v10, v10, v107, v26
	v_fma_f32 v11, v11, v107, v27
	global_load_dwordx4 v[82:85], v1, s[70:71]
	s_add_u32 s70, s70, 0x200000
	s_addc_u32 s71, s71, 0
	global_load_dword v107, v2, s[100:101]
	s_add_u32 s100, s100, 0x400
	s_addc_u32 s101, s101, 0
	s_waitcnt vmcnt(44)
; __device__ __forceinline__ unsigned pk2(float lo, float hi) { const f32x2_t_ v = {lo, hi}; return __builtin_bit_cast(unsigned, __builtin_convertvector(v, bf16x2_t_)); }
; __device__ __forceinline__ void ssd_s2_phase(Frame& F, bf16* states, const float* decay) {
;     ...
;         for (int c = 0; c < 64; ++c) { const v4u q = sp[(size_t)c * (128 * 64 * 16)]; const float dec = decay[(c * 8 + (h >> 4)) * 32 + (h & 15)];
;             v4u o; o.x = pk2(H[0], H[1]); o.y = pk2(H[2], H[3]); o.z = pk2(H[4], H[5]); o.w = pk2(H[6], H[7]);
;             sp[(size_t)c * (128 * 64 * 16)] = o;
;             H[0] = H[0] * dec + bflo(q.x); H[1] = H[1] * dec + bfhi(q.x); H[2] = H[2] * dec + bflo(q.y); H[3] = H[3] * dec + bfhi(q.y);
;             H[4] = H[4] * dec + bflo(q.z); H[5] = H[5] * dec + bfhi(q.z); H[6] = H[6] * dec + bflo(q.w); H[7] = H[7] * dec + bfhi(q.w); }
	v_cvt_pk_bf16_f32 v12, v4, v5
	v_cvt_pk_bf16_f32 v13, v6, v7
	v_cvt_pk_bf16_f32 v14, v8, v9
	v_cvt_pk_bf16_f32 v15, v10, v11
	global_store_dwordx4 v1, v[12:15], s[72:73]
	s_add_u32 s72, s72, 0x200000
	s_addc_u32 s73, s73, 0
	v_lshlrev_b32_e32 v20, 16, v86
	v_and_b32_e32 v21, 0xffff0000, v86
	v_lshlrev_b32_e32 v22, 16, v87
	v_and_b32_e32 v23, 0xffff0000, v87
	v_lshlrev_b32_e32 v24, 16, v88
	v_and_b32_e32 v25, 0xffff0000, v88
	v_lshlrev_b32_e32 v26, 16, v89
	v_and_b32_e32 v27, 0xffff0000, v89
	v_fma_f32 v4, v4, v108, v20
	v_fma_f32 v5, v5, v108, v21
	v_fma_f32 v6, v6, v108, v22
	v_fma_f32 v7, v7, v108, v23
	v_fma_f32 v8, v8, v108, v24
	v_fma_f32 v9, v9, v108, v25
	v_fma_f32 v10, v10, v108, v26
	v_fma_f32 v11, v11, v108, v27
	global_load_dwordx4 v[86:89], v1, s[70:71]
	s_add_u32 s70, s70, 0x200000
	s_addc_u32 s71, s71, 0
	global_load_dword v108, v2, s[100:101]
	s_add_u32 s100, s100, 0x400
	s_addc_u32 s101, s101, 0
	s_waitcnt vmcnt(45)
	v_cvt_pk_bf16_f32 v16, v4, v5
	v_cvt_pk_bf16_f32 v17, v6, v7
	v_cvt_pk_bf16_f32 v18, v8, v9
	v_cvt_pk_bf16_f32 v19, v10, v11
	global_store_dwordx4 v1, v[16:19], s[72:73]
	s_add_u32 s72, s72, 0x200000
	s_addc_u32 s73, s73, 0
	v_lshlrev_b32_e32 v20, 16, v90
	v_and_b32_e32 v21, 0xffff0000, v90
	v_lshlrev_b32_e32 v22, 16, v91
	v_and_b32_e32 v23, 0xffff0000, v91
	v_lshlrev_b32_e32 v24, 16, v92
	v_and_b32_e32 v25, 0xffff0000, v92
	v_lshlrev_b32_e32 v26, 16, v93
	v_and_b32_e32 v27, 0xffff0000, v93
	v_fma_f32 v4, v4, v109, v20
	v_fma_f32 v5, v5, v109, v21
	v_fma_f32 v6, v6, v109, v22
	v_fma_f32 v7, v7, v109, v23
	v_fma_f32 v8, v8, v109, v24
	v_fma_f32 v9, v9, v109, v25
	v_fma_f32 v10, v10, v109, v26
	v_fma_f32 v11, v11, v109, v27
	global_load_dwordx4 v[90:93], v1, s[70:71]
	s_add_u32 s70, s70, 0x200000
	s_addc_u32 s71, s71, 0
	global_load_dword v109, v2, s[100:101]
	s_add_u32 s100, s100, 0x400
	s_addc_u32 s101, s101, 0
	s_waitcnt vmcnt(45)
	v_cvt_pk_bf16_f32 v12, v4, v5
	v_cvt_pk_bf16_f32 v13, v6, v7
	v_cvt_pk_bf16_f32 v14, v8, v9
	v_cvt_pk_bf16_f32 v15, v10, v11
	global_store_dwordx4 v1, v[12:15], s[72:73]
	s_add_u32 s72, s72, 0x200000
	s_addc_u32 s73, s73, 0
	v_lshlrev_b32_e32 v20, 16, v30
	v_and_b32_e32 v21, 0xffff0000, v30
	v_lshlrev_b32_e32 v22, 16, v31
	v_and_b32_e32 v23, 0xffff0000, v31
	v_lshlrev_b32_e32 v24, 16, v32
	v_and_b32_e32 v25, 0xffff0000, v32
	v_lshlrev_b32_e32 v26, 16, v33
	v_and_b32_e32 v27, 0xffff0000, v33
	v_fma_f32 v4, v4, v94, v20
	v_fma_f32 v5, v5, v94, v21
	v_fma_f32 v6, v6, v94, v22
	v_fma_f32 v7, v7, v94, v23
	v_fma_f32 v8, v8, v94, v24
	v_fma_f32 v9, v9, v94, v25
	v_fma_f32 v10, v10, v94, v26
	v_fma_f32 v11, v11, v94, v27
	global_load_dwordx4 v[30:33], v1, s[70:71]
	s_add_u32 s70, s70, 0x200000
	s_addc_u32 s71, s71, 0
	global_load_dword v94, v2, s[100:101]
	s_add_u32 s100, s100, 0x400
	s_addc_u32 s101, s101, 0
	s_waitcnt vmcnt(45)
	v_cvt_pk_bf16_f32 v16, v4, v5
	v_cvt_pk_bf16_f32 v17, v6, v7
	v_cvt_pk_bf16_f32 v18, v8, v9
	v_cvt_pk_bf16_f32 v19, v10, v11
	global_store_dwordx4 v1, v[16:19], s[72:73]
	s_add_u32 s72, s72, 0x200000
	s_addc_u32 s73, s73, 0
	v_lshlrev_b32_e32 v20, 16, v34
	v_and_b32_e32 v21, 0xffff0000, v34
	v_lshlrev_b32_e32 v22, 16, v35
	v_and_b32_e32 v23, 0xffff0000, v35
	v_lshlrev_b32_e32 v24, 16, v36
	v_and_b32_e32 v25, 0xffff0000, v36
	v_lshlrev_b32_e32 v26, 16, v37
	v_and_b32_e32 v27, 0xffff0000, v37
	v_fma_f32 v4, v4, v95, v20
	v_fma_f32 v5, v5, v95, v21
	v_fma_f32 v6, v6, v95, v22
	v_fma_f32 v7, v7, v95, v23
	v_fma_f32 v8, v8, v95, v24
	v_fma_f32 v9, v9, v95, v25
	v_fma_f32 v10, v10, v95, v26
	v_fma_f32 v11, v11, v95, v27
	global_load_dwordx4 v[34:37], v1, s[70:71]
	s_add_u32 s70, s70, 0x200000
	s_addc_u32 s71, s71, 0
	global_load_dword v95, v2, s[100:101]
	s_add_u32 s100, s100, 0x400
	s_addc_u32 s101, s101, 0
	s_waitcnt vmcnt(45)
	v_cvt_pk_bf16_f32 v12, v4, v5
	v_cvt_pk_bf16_f32 v13, v6, v7
	v_cvt_pk_bf16_f32 v14, v8, v9
	v_cvt_pk_bf16_f32 v15, v10, v11
	global_store_dwordx4 v1, v[12:15], s[72:73]
	s_add_u32 s72, s72, 0x200000
	s_addc_u32 s73, s73, 0
	v_lshlrev_b32_e32 v20, 16, v38
	v_and_b32_e32 v21, 0xffff0000, v38
	v_lshlrev_b32_e32 v22, 16, v39
	v_and_b32_e32 v23, 0xffff0000, v39
	v_lshlrev_b32_e32 v24, 16, v40
	v_and_b32_e32 v25, 0xffff0000, v40
	v_lshlrev_b32_e32 v26, 16, v41
	v_and_b32_e32 v27, 0xffff0000, v41
	v_fma_f32 v4, v4, v96, v20
	v_fma_f32 v5, v5, v96, v21
	v_fma_f32 v6, v6, v96, v22
	v_fma_f32 v7, v7, v96, v23
	v_fma_f32 v8, v8, v96, v24
	v_fma_f32 v9, v9, v96, v25
	v_fma_f32 v10, v10, v96, v26
	v_fma_f32 v11, v11, v96, v27
	global_load_dwordx4 v[38:41], v1, s[70:71]
	s_add_u32 s70, s70, 0x200000
	s_addc_u32 s71, s71, 0
	global_load_dword v96, v2, s[100:101]
	s_add_u32 s100, s100, 0x400
	s_addc_u32 s101, s101, 0
	s_waitcnt vmcnt(45)
	v_cvt_pk_bf16_f32 v16, v4, v5
	v_cvt_pk_bf16_f32 v17, v6, v7
	v_cvt_pk_bf16_f32 v18, v8, v9
	v_cvt_pk_bf16_f32 v19, v10, v11
	global_store_dwordx4 v1, v[16:19], s[72:73]
	s_add_u32 s72, s72, 0x200000
	s_addc_u32 s73, s73, 0
	v_lshlrev_b32_e32 v20, 16, v42
	v_and_b32_e32 v21, 0xffff0000, v42
	v_lshlrev_b32_e32 v22, 16, v43
	v_and_b32_e32 v23, 0xffff0000, v43
	v_lshlrev_b32_e32 v24, 16, v44
	v_and_b32_e32 v25, 0xffff0000, v44
	v_lshlrev_b32_e32 v26, 16, v45
	v_and_b32_e32 v27, 0xffff0000, v45
	v_fma_f32 v4, v4, v97, v20
	v_fma_f32 v5, v5, v97, v21
	v_fma_f32 v6, v6, v97, v22
	v_fma_f32 v7, v7, v97, v23
	v_fma_f32 v8, v8, v97, v24
	v_fma_f32 v9, v9, v97, v25
	v_fma_f32 v10, v10, v97, v26
	v_fma_f32 v11, v11, v97, v27
	global_load_dwordx4 v[42:45], v1, s[70:71]
	s_add_u32 s70, s70, 0x200000
	s_addc_u32 s71, s71, 0
	global_load_dword v97, v2, s[100:101]
	s_add_u32 s100, s100, 0x400
	s_addc_u32 s101, s101, 0
	s_waitcnt vmcnt(45)
; __device__ __forceinline__ unsigned pk2(float lo, float hi) { const f32x2_t_ v = {lo, hi}; return __builtin_bit_cast(unsigned, __builtin_convertvector(v, bf16x2_t_)); }
; __device__ __forceinline__ void ssd_s2_phase(Frame& F, bf16* states, const float* decay) {
;     ...
;         for (int c = 0; c < 64; ++c) { const v4u q = sp[(size_t)c * (128 * 64 * 16)]; const float dec = decay[(c * 8 + (h >> 4)) * 32 + (h & 15)];
;             v4u o; o.x = pk2(H[0], H[1]); o.y = pk2(H[2], H[3]); o.z = pk2(H[4], H[5]); o.w = pk2(H[6], H[7]);
;             sp[(size_t)c * (128 * 64 * 16)] = o;
;             H[0] = H[0] * dec + bflo(q.x); H[1] = H[1] * dec + bfhi(q.x); H[2] = H[2] * dec + bflo(q.y); H[3] = H[3] * dec + bfhi(q.y);
;             H[4] = H[4] * dec + bflo(q.z); H[5] = H[5] * dec + bfhi(q.z); H[6] = H[6] * dec + bflo(q.w); H[7] = H[7] * dec + bfhi(q.w); }
	v_cvt_pk_bf16_f32 v12, v4, v5
	v_cvt_pk_bf16_f32 v13, v6, v7
	v_cvt_pk_bf16_f32 v14, v8, v9
	v_cvt_pk_bf16_f32 v15, v10, v11
	global_store_dwordx4 v1, v[12:15], s[72:73]
	s_add_u32 s72, s72, 0x200000
	s_addc_u32 s73, s73, 0
	v_lshlrev_b32_e32 v20, 16, v46
	v_and_b32_e32 v21, 0xffff0000, v46
	v_lshlrev_b32_e32 v22, 16, v47
	v_and_b32_e32 v23, 0xffff0000, v47
	v_lshlrev_b32_e32 v24, 16, v48
	v_and_b32_e32 v25, 0xffff0000, v48
	v_lshlrev_b32_e32 v26, 16, v49
	v_and_b32_e32 v27, 0xffff0000, v49
	v_fma_f32 v4, v4, v98, v20
	v_fma_f32 v5, v5, v98, v21
	v_fma_f32 v6, v6, v98, v22
	v_fma_f32 v7, v7, v98, v23
	v_fma_f32 v8, v8, v98, v24
	v_fma_f32 v9, v9, v98, v25
	v_fma_f32 v10, v10, v98, v26
	v_fma_f32 v11, v11, v98, v27
	global_load_dwordx4 v[46:49], v1, s[70:71]
	s_add_u32 s70, s70, 0x200000
	s_addc_u32 s71, s71, 0
	global_load_dword v98, v2, s[100:101]
	s_add_u32 s100, s100, 0x400
	s_addc_u32 s101, s101, 0
	s_waitcnt vmcnt(45)
	v_cvt_pk_bf16_f32 v16, v4, v5
	v_cvt_pk_bf16_f32 v17, v6, v7
	v_cvt_pk_bf16_f32 v18, v8, v9
	v_cvt_pk_bf16_f32 v19, v10, v11
	global_store_dwordx4 v1, v[16:19], s[72:73]
	s_add_u32 s72, s72, 0x200000
	s_addc_u32 s73, s73, 0
	v_lshlrev_b32_e32 v20, 16, v50
	v_and_b32_e32 v21, 0xffff0000, v50
	v_lshlrev_b32_e32 v22, 16, v51
	v_and_b32_e32 v23, 0xffff0000, v51
	v_lshlrev_b32_e32 v24, 16, v52
	v_and_b32_e32 v25, 0xffff0000, v52
	v_lshlrev_b32_e32 v26, 16, v53
	v_and_b32_e32 v27, 0xffff0000, v53
	v_fma_f32 v4, v4, v99, v20
	v_fma_f32 v5, v5, v99, v21
	v_fma_f32 v6, v6, v99, v22
	v_fma_f32 v7, v7, v99, v23
	v_fma_f32 v8, v8, v99, v24
	v_fma_f32 v9, v9, v99, v25
	v_fma_f32 v10, v10, v99, v26
	v_fma_f32 v11, v11, v99, v27
	global_load_dwordx4 v[50:53], v1, s[70:71]
	s_add_u32 s70, s70, 0x200000
	s_addc_u32 s71, s71, 0
	global_load_dword v99, v2, s[100:101]
	s_add_u32 s100, s100, 0x400
	s_addc_u32 s101, s101, 0
	s_waitcnt vmcnt(45)
	v_cvt_pk_bf16_f32 v12, v4, v5
	v_cvt_pk_bf16_f32 v13, v6, v7
	v_cvt_pk_bf16_f32 v14, v8, v9
	v_cvt_pk_bf16_f32 v15, v10, v11
	global_store_dwordx4 v1, v[12:15], s[72:73]
	s_add_u32 s72, s72, 0x200000
	s_addc_u32 s73, s73, 0
	v_lshlrev_b32_e32 v20, 16, v54
	v_and_b32_e32 v21, 0xffff0000, v54
	v_lshlrev_b32_e32 v22, 16, v55
	v_and_b32_e32 v23, 0xffff0000, v55
	v_lshlrev_b32_e32 v24, 16, v56
	v_and_b32_e32 v25, 0xffff0000, v56
	v_lshlrev_b32_e32 v26, 16, v57
	v_and_b32_e32 v27, 0xffff0000, v57
	v_fma_f32 v4, v4, v100, v20
	v_fma_f32 v5, v5, v100, v21
	v_fma_f32 v6, v6, v100, v22
	v_fma_f32 v7, v7, v100, v23
	v_fma_f32 v8, v8, v100, v24
	v_fma_f32 v9, v9, v100, v25
	v_fma_f32 v10, v10, v100, v26
	v_fma_f32 v11, v11, v100, v27
	global_load_dwordx4 v[54:57], v1, s[70:71]
	s_add_u32 s70, s70, 0x200000
	s_addc_u32 s71, s71, 0
	global_load_dword v100, v2, s[100:101]
	s_add_u32 s100, s100, 0x400
	s_addc_u32 s101, s101, 0
	s_waitcnt vmcnt(45)
	v_cvt_pk_bf16_f32 v16, v4, v5
	v_cvt_pk_bf16_f32 v17, v6, v7
	v_cvt_pk_bf16_f32 v18, v8, v9
	v_cvt_pk_bf16_f32 v19, v10, v11
	global_store_dwordx4 v1, v[16:19], s[72:73]
	s_add_u32 s72, s72, 0x200000
	s_addc_u32 s73, s73, 0
	v_lshlrev_b32_e32 v20, 16, v58
	v_and_b32_e32 v21, 0xffff0000, v58
	v_lshlrev_b32_e32 v22, 16, v59
	v_and_b32_e32 v23, 0xffff0000, v59
	v_lshlrev_b32_e32 v24, 16, v60
	v_and_b32_e32 v25, 0xffff0000, v60
	v_lshlrev_b32_e32 v26, 16, v61
	v_and_b32_e32 v27, 0xffff0000, v61
	v_fma_f32 v4, v4, v101, v20
	v_fma_f32 v5, v5, v101, v21
	v_fma_f32 v6, v6, v101, v22
	v_fma_f32 v7, v7, v101, v23
	v_fma_f32 v8, v8, v101, v24
	v_fma_f32 v9, v9, v101, v25
	v_fma_f32 v10, v10, v101, v26
	v_fma_f32 v11, v11, v101, v27
	global_load_dwordx4 v[58:61], v1, s[70:71]
	s_add_u32 s70, s70, 0x200000
	s_addc_u32 s71, s71, 0
	global_load_dword v101, v2, s[100:101]
	s_add_u32 s100, s100, 0x400
	s_addc_u32 s101, s101, 0
	s_waitcnt vmcnt(45)
	v_cvt_pk_bf16_f32 v12, v4, v5
	v_cvt_pk_bf16_f32 v13, v6, v7
	v_cvt_pk_bf16_f32 v14, v8, v9
	v_cvt_pk_bf16_f32 v15, v10, v11
	global_store_dwordx4 v1, v[12:15], s[72:73]
	s_add_u32 s72, s72, 0x200000
	s_addc_u32 s73, s73, 0
	v_lshlrev_b32_e32 v20, 16, v62
	v_and_b32_e32 v21, 0xffff0000, v62
	v_lshlrev_b32_e32 v22, 16, v63
	v_and_b32_e32 v23, 0xffff0000, v63
	v_lshlrev_b32_e32 v24, 16, v64
	v_and_b32_e32 v25, 0xffff0000, v64
	v_lshlrev_b32_e32 v26, 16, v65
	v_and_b32_e32 v27, 0xffff0000, v65
	v_fma_f32 v4, v4, v102, v20
	v_fma_f32 v5, v5, v102, v21
	v_fma_f32 v6, v6, v102, v22
	v_fma_f32 v7, v7, v102, v23
	v_fma_f32 v8, v8, v102, v24
	v_fma_f32 v9, v9, v102, v25
	v_fma_f32 v10, v10, v102, v26
	v_fma_f32 v11, v11, v102, v27
	global_load_dwordx4 v[62:65], v1, s[70:71]
	s_add_u32 s70, s70, 0x200000
	s_addc_u32 s71, s71, 0
	global_load_dword v102, v2, s[100:101]
	s_add_u32 s100, s100, 0x400
	s_addc_u32 s101, s101, 0
	s_waitcnt vmcnt(45)
	v_cvt_pk_bf16_f32 v16, v4, v5
	v_cvt_pk_bf16_f32 v17, v6, v7
	v_cvt_pk_bf16_f32 v18, v8, v9
	v_cvt_pk_bf16_f32 v19, v10, v11
	global_store_dwordx4 v1, v[16:19], s[72:73]
	s_add_u32 s72, s72, 0x200000
	s_addc_u32 s73, s73, 0
	v_lshlrev_b32_e32 v20, 16, v66
	v_and_b32_e32 v21, 0xffff0000, v66
	v_lshlrev_b32_e32 v22, 16, v67
	v_and_b32_e32 v23, 0xffff0000, v67
	v_lshlrev_b32_e32 v24, 16, v68
	v_and_b32_e32 v25, 0xffff0000, v68
	v_lshlrev_b32_e32 v26, 16, v69
	v_and_b32_e32 v27, 0xffff0000, v69
	v_fma_f32 v4, v4, v103, v20
	v_fma_f32 v5, v5, v103, v21
	v_fma_f32 v6, v6, v103, v22
	v_fma_f32 v7, v7, v103, v23
	v_fma_f32 v8, v8, v103, v24
	v_fma_f32 v9, v9, v103, v25
	v_fma_f32 v10, v10, v103, v26
	v_fma_f32 v11, v11, v103, v27
	global_load_dwordx4 v[66:69], v1, s[70:71]
	s_add_u32 s70, s70, 0x200000
	s_addc_u32 s71, s71, 0
	global_load_dword v103, v2, s[100:101]
	s_add_u32 s100, s100, 0x400
	s_addc_u32 s101, s101, 0
	s_waitcnt vmcnt(45)
; __device__ __forceinline__ unsigned pk2(float lo, float hi) { const f32x2_t_ v = {lo, hi}; return __builtin_bit_cast(unsigned, __builtin_convertvector(v, bf16x2_t_)); }
; __device__ __forceinline__ void ssd_s2_phase(Frame& F, bf16* states, const float* decay) {
;     ...
;         for (int c = 0; c < 64; ++c) { const v4u q = sp[(size_t)c * (128 * 64 * 16)]; const float dec = decay[(c * 8 + (h >> 4)) * 32 + (h & 15)];
;             v4u o; o.x = pk2(H[0], H[1]); o.y = pk2(H[2], H[3]); o.z = pk2(H[4], H[5]); o.w = pk2(H[6], H[7]);
;             sp[(size_t)c * (128 * 64 * 16)] = o;
;             H[0] = H[0] * dec + bflo(q.x); H[1] = H[1] * dec + bfhi(q.x); H[2] = H[2] * dec + bflo(q.y); H[3] = H[3] * dec + bfhi(q.y);
;             H[4] = H[4] * dec + bflo(q.z); H[5] = H[5] * dec + bfhi(q.z); H[6] = H[6] * dec + bflo(q.w); H[7] = H[7] * dec + bfhi(q.w); }
	v_cvt_pk_bf16_f32 v12, v4, v5
	v_cvt_pk_bf16_f32 v13, v6, v7
	v_cvt_pk_bf16_f32 v14, v8, v9
	v_cvt_pk_bf16_f32 v15, v10, v11
	global_store_dwordx4 v1, v[12:15], s[72:73]
	s_add_u32 s72, s72, 0x200000
	s_addc_u32 s73, s73, 0
	v_lshlrev_b32_e32 v20, 16, v70
	v_and_b32_e32 v21, 0xffff0000, v70
	v_lshlrev_b32_e32 v22, 16, v71
	v_and_b32_e32 v23, 0xffff0000, v71
	v_lshlrev_b32_e32 v24, 16, v72
	v_and_b32_e32 v25, 0xffff0000, v72
	v_lshlrev_b32_e32 v26, 16, v73
	v_and_b32_e32 v27, 0xffff0000, v73
	v_fma_f32 v4, v4, v104, v20
	v_fma_f32 v5, v5, v104, v21
	v_fma_f32 v6, v6, v104, v22
	v_fma_f32 v7, v7, v104, v23
	v_fma_f32 v8, v8, v104, v24
	v_fma_f32 v9, v9, v104, v25
	v_fma_f32 v10, v10, v104, v26
	v_fma_f32 v11, v11, v104, v27
	global_load_dwordx4 v[70:73], v1, s[70:71]
	s_add_u32 s70, s70, 0x200000
	s_addc_u32 s71, s71, 0
	global_load_dword v104, v2, s[100:101]
	s_add_u32 s100, s100, 0x400
	s_addc_u32 s101, s101, 0
	s_waitcnt vmcnt(45)
	v_cvt_pk_bf16_f32 v16, v4, v5
	v_cvt_pk_bf16_f32 v17, v6, v7
	v_cvt_pk_bf16_f32 v18, v8, v9
	v_cvt_pk_bf16_f32 v19, v10, v11
	global_store_dwordx4 v1, v[16:19], s[72:73]
	s_add_u32 s72, s72, 0x200000
	s_addc_u32 s73, s73, 0
	v_lshlrev_b32_e32 v20, 16, v74
	v_and_b32_e32 v21, 0xffff0000, v74
	v_lshlrev_b32_e32 v22, 16, v75
	v_and_b32_e32 v23, 0xffff0000, v75
	v_lshlrev_b32_e32 v24, 16, v76
	v_and_b32_e32 v25, 0xffff0000, v76
	v_lshlrev_b32_e32 v26, 16, v77
	v_and_b32_e32 v27, 0xffff0000, v77
	v_fma_f32 v4, v4, v105, v20
	v_fma_f32 v5, v5, v105, v21
	v_fma_f32 v6, v6, v105, v22
	v_fma_f32 v7, v7, v105, v23
	v_fma_f32 v8, v8, v105, v24
	v_fma_f32 v9, v9, v105, v25
	v_fma_f32 v10, v10, v105, v26
	v_fma_f32 v11, v11, v105, v27
	global_load_dwordx4 v[74:77], v1, s[70:71]
	s_add_u32 s70, s70, 0x200000
	s_addc_u32 s71, s71, 0
	global_load_dword v105, v2, s[100:101]
	s_add_u32 s100, s100, 0x400
	s_addc_u32 s101, s101, 0
	s_waitcnt vmcnt(45)
	v_cvt_pk_bf16_f32 v12, v4, v5
	v_cvt_pk_bf16_f32 v13, v6, v7
	v_cvt_pk_bf16_f32 v14, v8, v9
	v_cvt_pk_bf16_f32 v15, v10, v11
	global_store_dwordx4 v1, v[12:15], s[72:73]
	s_add_u32 s72, s72, 0x200000
	s_addc_u32 s73, s73, 0
	v_lshlrev_b32_e32 v20, 16, v78
	v_and_b32_e32 v21, 0xffff0000, v78
	v_lshlrev_b32_e32 v22, 16, v79
	v_and_b32_e32 v23, 0xffff0000, v79
	v_lshlrev_b32_e32 v24, 16, v80
	v_and_b32_e32 v25, 0xffff0000, v80
	v_lshlrev_b32_e32 v26, 16, v81
	v_and_b32_e32 v27, 0xffff0000, v81
	v_fma_f32 v4, v4, v106, v20
	v_fma_f32 v5, v5, v106, v21
	v_fma_f32 v6, v6, v106, v22
	v_fma_f32 v7, v7, v106, v23
	v_fma_f32 v8, v8, v106, v24
	v_fma_f32 v9, v9, v106, v25
	v_fma_f32 v10, v10, v106, v26
	v_fma_f32 v11, v11, v106, v27
	global_load_dwordx4 v[78:81], v1, s[70:71]
	s_add_u32 s70, s70, 0x200000
	s_addc_u32 s71, s71, 0
	global_load_dword v106, v2, s[100:101]
	s_add_u32 s100, s100, 0x400
	s_addc_u32 s101, s101, 0
	s_waitcnt vmcnt(45)
	v_cvt_pk_bf16_f32 v16, v4, v5
	v_cvt_pk_bf16_f32 v17, v6, v7
	v_cvt_pk_bf16_f32 v18, v8, v9
	v_cvt_pk_bf16_f32 v19, v10, v11
	global_store_dwordx4 v1, v[16:19], s[72:73]
	s_add_u32 s72, s72, 0x200000
	s_addc_u32 s73, s73, 0
	v_lshlrev_b32_e32 v20, 16, v82
	v_and_b32_e32 v21, 0xffff0000, v82
	v_lshlrev_b32_e32 v22, 16, v83
	v_and_b32_e32 v23, 0xffff0000, v83
	v_lshlrev_b32_e32 v24, 16, v84
	v_and_b32_e32 v25, 0xffff0000, v84
	v_lshlrev_b32_e32 v26, 16, v85
	v_and_b32_e32 v27, 0xffff0000, v85
	v_fma_f32 v4, v4, v107, v20
	v_fma_f32 v5, v5, v107, v21
	v_fma_f32 v6, v6, v107, v22
	v_fma_f32 v7, v7, v107, v23
	v_fma_f32 v8, v8, v107, v24
	v_fma_f32 v9, v9, v107, v25
	v_fma_f32 v10, v10, v107, v26
	v_fma_f32 v11, v11, v107, v27
	global_load_dwordx4 v[82:85], v1, s[70:71]
	s_add_u32 s70, s70, 0x200000
	s_addc_u32 s71, s71, 0
	global_load_dword v107, v2, s[100:101]
	s_add_u32 s100, s100, 0x400
	s_addc_u32 s101, s101, 0
	s_waitcnt vmcnt(45)
	v_cvt_pk_bf16_f32 v12, v4, v5
	v_cvt_pk_bf16_f32 v13, v6, v7
	v_cvt_pk_bf16_f32 v14, v8, v9
	v_cvt_pk_bf16_f32 v15, v10, v11
	global_store_dwordx4 v1, v[12:15], s[72:73]
	s_add_u32 s72, s72, 0x200000
	s_addc_u32 s73, s73, 0
	v_lshlrev_b32_e32 v20, 16, v86
	v_and_b32_e32 v21, 0xffff0000, v86
	v_lshlrev_b32_e32 v22, 16, v87
	v_and_b32_e32 v23, 0xffff0000, v87
	v_lshlrev_b32_e32 v24, 16, v88
	v_and_b32_e32 v25, 0xffff0000, v88
	v_lshlrev_b32_e32 v26, 16, v89
	v_and_b32_e32 v27, 0xffff0000, v89
	v_fma_f32 v4, v4, v108, v20
	v_fma_f32 v5, v5, v108, v21
	v_fma_f32 v6, v6, v108, v22
	v_fma_f32 v7, v7, v108, v23
	v_fma_f32 v8, v8, v108, v24
	v_fma_f32 v9, v9, v108, v25
	v_fma_f32 v10, v10, v108, v26
	v_fma_f32 v11, v11, v108, v27
	global_load_dwordx4 v[86:89], v1, s[70:71]
	s_add_u32 s70, s70, 0x200000
	s_addc_u32 s71, s71, 0
	global_load_dword v108, v2, s[100:101]
	s_add_u32 s100, s100, 0x400
	s_addc_u32 s101, s101, 0
	s_waitcnt vmcnt(45)
	v_cvt_pk_bf16_f32 v16, v4, v5
	v_cvt_pk_bf16_f32 v17, v6, v7
	v_cvt_pk_bf16_f32 v18, v8, v9
	v_cvt_pk_bf16_f32 v19, v10, v11
	global_store_dwordx4 v1, v[16:19], s[72:73]
	s_add_u32 s72, s72, 0x200000
	s_addc_u32 s73, s73, 0
	v_lshlrev_b32_e32 v20, 16, v90
	v_and_b32_e32 v21, 0xffff0000, v90
	v_lshlrev_b32_e32 v22, 16, v91
	v_and_b32_e32 v23, 0xffff0000, v91
	v_lshlrev_b32_e32 v24, 16, v92
	v_and_b32_e32 v25, 0xffff0000, v92
	v_lshlrev_b32_e32 v26, 16, v93
	v_and_b32_e32 v27, 0xffff0000, v93
	v_fma_f32 v4, v4, v109, v20
	v_fma_f32 v5, v5, v109, v21
	v_fma_f32 v6, v6, v109, v22
	v_fma_f32 v7, v7, v109, v23
	v_fma_f32 v8, v8, v109, v24
	v_fma_f32 v9, v9, v109, v25
	v_fma_f32 v10, v10, v109, v26
	v_fma_f32 v11, v11, v109, v27
	global_load_dwordx4 v[90:93], v1, s[70:71]
	s_add_u32 s70, s70, 0x200000
	s_addc_u32 s71, s71, 0
	global_load_dword v109, v2, s[100:101]
	s_add_u32 s100, s100, 0x400
	s_addc_u32 s101, s101, 0
	s_waitcnt vmcnt(45)
; __device__ __forceinline__ unsigned pk2(float lo, float hi) { const f32x2_t_ v = {lo, hi}; return __builtin_bit_cast(unsigned, __builtin_convertvector(v, bf16x2_t_)); }
; __device__ __forceinline__ void ssd_s2_phase(Frame& F, bf16* states, const float* decay) {
;     ...
;         for (int c = 0; c < 64; ++c) { const v4u q = sp[(size_t)c * (128 * 64 * 16)]; const float dec = decay[(c * 8 + (h >> 4)) * 32 + (h & 15)];
;             v4u o; o.x = pk2(H[0], H[1]); o.y = pk2(H[2], H[3]); o.z = pk2(H[4], H[5]); o.w = pk2(H[6], H[7]);
;             sp[(size_t)c * (128 * 64 * 16)] = o;
;             H[0] = H[0] * dec + bflo(q.x); H[1] = H[1] * dec + bfhi(q.x); H[2] = H[2] * dec + bflo(q.y); H[3] = H[3] * dec + bfhi(q.y);
;             H[4] = H[4] * dec + bflo(q.z); H[5] = H[5] * dec + bfhi(q.z); H[6] = H[6] * dec + bflo(q.w); H[7] = H[7] * dec + bfhi(q.w); }
	v_cvt_pk_bf16_f32 v12, v4, v5
	v_cvt_pk_bf16_f32 v13, v6, v7
	v_cvt_pk_bf16_f32 v14, v8, v9
	v_cvt_pk_bf16_f32 v15, v10, v11
	global_store_dwordx4 v1, v[12:15], s[72:73]
	s_add_u32 s72, s72, 0x200000
	s_addc_u32 s73, s73, 0
	v_lshlrev_b32_e32 v20, 16, v30
	v_and_b32_e32 v21, 0xffff0000, v30
	v_lshlrev_b32_e32 v22, 16, v31
	v_and_b32_e32 v23, 0xffff0000, v31
	v_lshlrev_b32_e32 v24, 16, v32
	v_and_b32_e32 v25, 0xffff0000, v32
	v_lshlrev_b32_e32 v26, 16, v33
	v_and_b32_e32 v27, 0xffff0000, v33
	v_fma_f32 v4, v4, v94, v20
	v_fma_f32 v5, v5, v94, v21
	v_fma_f32 v6, v6, v94, v22
	v_fma_f32 v7, v7, v94, v23
	v_fma_f32 v8, v8, v94, v24
	v_fma_f32 v9, v9, v94, v25
	v_fma_f32 v10, v10, v94, v26
	v_fma_f32 v11, v11, v94, v27
	global_load_dwordx4 v[30:33], v1, s[70:71]
	s_add_u32 s70, s70, 0x200000
	s_addc_u32 s71, s71, 0
	global_load_dword v94, v2, s[100:101]
	s_add_u32 s100, s100, 0x400
	s_addc_u32 s101, s101, 0
	s_waitcnt vmcnt(45)
	v_cvt_pk_bf16_f32 v16, v4, v5
	v_cvt_pk_bf16_f32 v17, v6, v7
	v_cvt_pk_bf16_f32 v18, v8, v9
	v_cvt_pk_bf16_f32 v19, v10, v11
	global_store_dwordx4 v1, v[16:19], s[72:73]
	s_add_u32 s72, s72, 0x200000
	s_addc_u32 s73, s73, 0
	v_lshlrev_b32_e32 v20, 16, v34
	v_and_b32_e32 v21, 0xffff0000, v34
	v_lshlrev_b32_e32 v22, 16, v35
	v_and_b32_e32 v23, 0xffff0000, v35
	v_lshlrev_b32_e32 v24, 16, v36
	v_and_b32_e32 v25, 0xffff0000, v36
	v_lshlrev_b32_e32 v26, 16, v37
	v_and_b32_e32 v27, 0xffff0000, v37
	v_fma_f32 v4, v4, v95, v20
	v_fma_f32 v5, v5, v95, v21
	v_fma_f32 v6, v6, v95, v22
	v_fma_f32 v7, v7, v95, v23
	v_fma_f32 v8, v8, v95, v24
	v_fma_f32 v9, v9, v95, v25
	v_fma_f32 v10, v10, v95, v26
	v_fma_f32 v11, v11, v95, v27
	global_load_dwordx4 v[34:37], v1, s[70:71]
	s_add_u32 s70, s70, 0x200000
	s_addc_u32 s71, s71, 0
	global_load_dword v95, v2, s[100:101]
	s_add_u32 s100, s100, 0x400
	s_addc_u32 s101, s101, 0
	s_waitcnt vmcnt(45)
	v_cvt_pk_bf16_f32 v12, v4, v5
	v_cvt_pk_bf16_f32 v13, v6, v7
	v_cvt_pk_bf16_f32 v14, v8, v9
	v_cvt_pk_bf16_f32 v15, v10, v11
	global_store_dwordx4 v1, v[12:15], s[72:73]
	s_add_u32 s72, s72, 0x200000
	s_addc_u32 s73, s73, 0
	v_lshlrev_b32_e32 v20, 16, v38
	v_and_b32_e32 v21, 0xffff0000, v38
	v_lshlrev_b32_e32 v22, 16, v39
	v_and_b32_e32 v23, 0xffff0000, v39
	v_lshlrev_b32_e32 v24, 16, v40
	v_and_b32_e32 v25, 0xffff0000, v40
	v_lshlrev_b32_e32 v26, 16, v41
	v_and_b32_e32 v27, 0xffff0000, v41
	v_fma_f32 v4, v4, v96, v20
	v_fma_f32 v5, v5, v96, v21
	v_fma_f32 v6, v6, v96, v22
	v_fma_f32 v7, v7, v96, v23
	v_fma_f32 v8, v8, v96, v24
	v_fma_f32 v9, v9, v96, v25
	v_fma_f32 v10, v10, v96, v26
	v_fma_f32 v11, v11, v96, v27
	global_load_dwordx4 v[38:41], v1, s[70:71]
	s_add_u32 s70, s70, 0x200000
	s_addc_u32 s71, s71, 0
	global_load_dword v96, v2, s[100:101]
	s_add_u32 s100, s100, 0x400
	s_addc_u32 s101, s101, 0
	s_waitcnt vmcnt(45)
	v_cvt_pk_bf16_f32 v16, v4, v5
	v_cvt_pk_bf16_f32 v17, v6, v7
	v_cvt_pk_bf16_f32 v18, v8, v9
	v_cvt_pk_bf16_f32 v19, v10, v11
	global_store_dwordx4 v1, v[16:19], s[72:73]
	s_add_u32 s72, s72, 0x200000
	s_addc_u32 s73, s73, 0
	v_lshlrev_b32_e32 v20, 16, v42
	v_and_b32_e32 v21, 0xffff0000, v42
	v_lshlrev_b32_e32 v22, 16, v43
	v_and_b32_e32 v23, 0xffff0000, v43
	v_lshlrev_b32_e32 v24, 16, v44
	v_and_b32_e32 v25, 0xffff0000, v44
	v_lshlrev_b32_e32 v26, 16, v45
	v_and_b32_e32 v27, 0xffff0000, v45
	v_fma_f32 v4, v4, v97, v20
	v_fma_f32 v5, v5, v97, v21
	v_fma_f32 v6, v6, v97, v22
	v_fma_f32 v7, v7, v97, v23
	v_fma_f32 v8, v8, v97, v24
	v_fma_f32 v9, v9, v97, v25
	v_fma_f32 v10, v10, v97, v26
	v_fma_f32 v11, v11, v97, v27
	global_load_dwordx4 v[42:45], v1, s[70:71]
	s_add_u32 s70, s70, 0x200000
	s_addc_u32 s71, s71, 0
	global_load_dword v97, v2, s[100:101]
	s_add_u32 s100, s100, 0x400
	s_addc_u32 s101, s101, 0
	s_waitcnt vmcnt(45)
	v_cvt_pk_bf16_f32 v12, v4, v5
	v_cvt_pk_bf16_f32 v13, v6, v7
	v_cvt_pk_bf16_f32 v14, v8, v9
	v_cvt_pk_bf16_f32 v15, v10, v11
	global_store_dwordx4 v1, v[12:15], s[72:73]
	s_add_u32 s72, s72, 0x200000
	s_addc_u32 s73, s73, 0
	v_lshlrev_b32_e32 v20, 16, v46
	v_and_b32_e32 v21, 0xffff0000, v46
	v_lshlrev_b32_e32 v22, 16, v47
	v_and_b32_e32 v23, 0xffff0000, v47
	v_lshlrev_b32_e32 v24, 16, v48
	v_and_b32_e32 v25, 0xffff0000, v48
	v_lshlrev_b32_e32 v26, 16, v49
	v_and_b32_e32 v27, 0xffff0000, v49
	v_fma_f32 v4, v4, v98, v20
	v_fma_f32 v5, v5, v98, v21
	v_fma_f32 v6, v6, v98, v22
	v_fma_f32 v7, v7, v98, v23
	v_fma_f32 v8, v8, v98, v24
	v_fma_f32 v9, v9, v98, v25
	v_fma_f32 v10, v10, v98, v26
	v_fma_f32 v11, v11, v98, v27
	global_load_dwordx4 v[46:49], v1, s[70:71]
	s_add_u32 s70, s70, 0x200000
	s_addc_u32 s71, s71, 0
	global_load_dword v98, v2, s[100:101]
	s_add_u32 s100, s100, 0x400
	s_addc_u32 s101, s101, 0
	s_waitcnt vmcnt(45)
	v_cvt_pk_bf16_f32 v16, v4, v5
	v_cvt_pk_bf16_f32 v17, v6, v7
	v_cvt_pk_bf16_f32 v18, v8, v9
	v_cvt_pk_bf16_f32 v19, v10, v11
	global_store_dwordx4 v1, v[16:19], s[72:73]
	s_add_u32 s72, s72, 0x200000
	s_addc_u32 s73, s73, 0
	v_lshlrev_b32_e32 v20, 16, v50
	v_and_b32_e32 v21, 0xffff0000, v50
	v_lshlrev_b32_e32 v22, 16, v51
	v_and_b32_e32 v23, 0xffff0000, v51
	v_lshlrev_b32_e32 v24, 16, v52
	v_and_b32_e32 v25, 0xffff0000, v52
	v_lshlrev_b32_e32 v26, 16, v53
	v_and_b32_e32 v27, 0xffff0000, v53
	v_fma_f32 v4, v4, v99, v20
	v_fma_f32 v5, v5, v99, v21
	v_fma_f32 v6, v6, v99, v22
	v_fma_f32 v7, v7, v99, v23
	v_fma_f32 v8, v8, v99, v24
	v_fma_f32 v9, v9, v99, v25
	v_fma_f32 v10, v10, v99, v26
	v_fma_f32 v11, v11, v99, v27
	global_load_dwordx4 v[50:53], v1, s[70:71]
	s_add_u32 s70, s70, 0x200000
	s_addc_u32 s71, s71, 0
	global_load_dword v99, v2, s[100:101]
	s_add_u32 s100, s100, 0x400
	s_addc_u32 s101, s101, 0
	s_waitcnt vmcnt(45)
; __device__ __forceinline__ unsigned pk2(float lo, float hi) { const f32x2_t_ v = {lo, hi}; return __builtin_bit_cast(unsigned, __builtin_convertvector(v, bf16x2_t_)); }
; __device__ __forceinline__ void ssd_s2_phase(Frame& F, bf16* states, const float* decay) {
;     ...
;         for (int c = 0; c < 64; ++c) { const v4u q = sp[(size_t)c * (128 * 64 * 16)]; const float dec = decay[(c * 8 + (h >> 4)) * 32 + (h & 15)];
;             v4u o; o.x = pk2(H[0], H[1]); o.y = pk2(H[2], H[3]); o.z = pk2(H[4], H[5]); o.w = pk2(H[6], H[7]);
;             sp[(size_t)c * (128 * 64 * 16)] = o;
;             H[0] = H[0] * dec + bflo(q.x); H[1] = H[1] * dec + bfhi(q.x); H[2] = H[2] * dec + bflo(q.y); H[3] = H[3] * dec + bfhi(q.y);
;             H[4] = H[4] * dec + bflo(q.z); H[5] = H[5] * dec + bfhi(q.z); H[6] = H[6] * dec + bflo(q.w); H[7] = H[7] * dec + bfhi(q.w); }
	v_cvt_pk_bf16_f32 v12, v4, v5
	v_cvt_pk_bf16_f32 v13, v6, v7
	v_cvt_pk_bf16_f32 v14, v8, v9
	v_cvt_pk_bf16_f32 v15, v10, v11
	global_store_dwordx4 v1, v[12:15], s[72:73]
	s_add_u32 s72, s72, 0x200000
	s_addc_u32 s73, s73, 0
	v_lshlrev_b32_e32 v20, 16, v54
	v_and_b32_e32 v21, 0xffff0000, v54
	v_lshlrev_b32_e32 v22, 16, v55
	v_and_b32_e32 v23, 0xffff0000, v55
	v_lshlrev_b32_e32 v24, 16, v56
	v_and_b32_e32 v25, 0xffff0000, v56
	v_lshlrev_b32_e32 v26, 16, v57
	v_and_b32_e32 v27, 0xffff0000, v57
	v_fma_f32 v4, v4, v100, v20
	v_fma_f32 v5, v5, v100, v21
	v_fma_f32 v6, v6, v100, v22
	v_fma_f32 v7, v7, v100, v23
	v_fma_f32 v8, v8, v100, v24
	v_fma_f32 v9, v9, v100, v25
	v_fma_f32 v10, v10, v100, v26
	v_fma_f32 v11, v11, v100, v27
	global_load_dwordx4 v[54:57], v1, s[70:71]
	s_add_u32 s70, s70, 0x200000
	s_addc_u32 s71, s71, 0
	global_load_dword v100, v2, s[100:101]
	s_add_u32 s100, s100, 0x400
	s_addc_u32 s101, s101, 0
	s_waitcnt vmcnt(45)
	v_cvt_pk_bf16_f32 v16, v4, v5
	v_cvt_pk_bf16_f32 v17, v6, v7
	v_cvt_pk_bf16_f32 v18, v8, v9
	v_cvt_pk_bf16_f32 v19, v10, v11
	global_store_dwordx4 v1, v[16:19], s[72:73]
	s_add_u32 s72, s72, 0x200000
	s_addc_u32 s73, s73, 0
	v_lshlrev_b32_e32 v20, 16, v58
	v_and_b32_e32 v21, 0xffff0000, v58
	v_lshlrev_b32_e32 v22, 16, v59
	v_and_b32_e32 v23, 0xffff0000, v59
	v_lshlrev_b32_e32 v24, 16, v60
	v_and_b32_e32 v25, 0xffff0000, v60
	v_lshlrev_b32_e32 v26, 16, v61
	v_and_b32_e32 v27, 0xffff0000, v61
	v_fma_f32 v4, v4, v101, v20
	v_fma_f32 v5, v5, v101, v21
	v_fma_f32 v6, v6, v101, v22
	v_fma_f32 v7, v7, v101, v23
	v_fma_f32 v8, v8, v101, v24
	v_fma_f32 v9, v9, v101, v25
	v_fma_f32 v10, v10, v101, v26
	v_fma_f32 v11, v11, v101, v27
	global_load_dwordx4 v[58:61], v1, s[70:71]
	s_add_u32 s70, s70, 0x200000
	s_addc_u32 s71, s71, 0
	global_load_dword v101, v2, s[100:101]
	s_add_u32 s100, s100, 0x400
	s_addc_u32 s101, s101, 0
	s_waitcnt vmcnt(45)
	v_cvt_pk_bf16_f32 v12, v4, v5
	v_cvt_pk_bf16_f32 v13, v6, v7
	v_cvt_pk_bf16_f32 v14, v8, v9
	v_cvt_pk_bf16_f32 v15, v10, v11
	global_store_dwordx4 v1, v[12:15], s[72:73]
	s_add_u32 s72, s72, 0x200000
	s_addc_u32 s73, s73, 0
	v_lshlrev_b32_e32 v20, 16, v62
	v_and_b32_e32 v21, 0xffff0000, v62
	v_lshlrev_b32_e32 v22, 16, v63
	v_and_b32_e32 v23, 0xffff0000, v63
	v_lshlrev_b32_e32 v24, 16, v64
	v_and_b32_e32 v25, 0xffff0000, v64
	v_lshlrev_b32_e32 v26, 16, v65
	v_and_b32_e32 v27, 0xffff0000, v65
	v_fma_f32 v4, v4, v102, v20
	v_fma_f32 v5, v5, v102, v21
	v_fma_f32 v6, v6, v102, v22
	v_fma_f32 v7, v7, v102, v23
	v_fma_f32 v8, v8, v102, v24
	v_fma_f32 v9, v9, v102, v25
	v_fma_f32 v10, v10, v102, v26
	v_fma_f32 v11, v11, v102, v27
	global_load_dwordx4 v[62:65], v1, s[70:71]
	s_add_u32 s70, s70, 0x200000
	s_addc_u32 s71, s71, 0
	global_load_dword v102, v2, s[100:101]
	s_add_u32 s100, s100, 0x400
	s_addc_u32 s101, s101, 0
	s_waitcnt vmcnt(45)
	v_cvt_pk_bf16_f32 v16, v4, v5
	v_cvt_pk_bf16_f32 v17, v6, v7
	v_cvt_pk_bf16_f32 v18, v8, v9
	v_cvt_pk_bf16_f32 v19, v10, v11
	global_store_dwordx4 v1, v[16:19], s[72:73]
	s_add_u32 s72, s72, 0x200000
	s_addc_u32 s73, s73, 0
	v_lshlrev_b32_e32 v20, 16, v66
	v_and_b32_e32 v21, 0xffff0000, v66
	v_lshlrev_b32_e32 v22, 16, v67
	v_and_b32_e32 v23, 0xffff0000, v67
	v_lshlrev_b32_e32 v24, 16, v68
	v_and_b32_e32 v25, 0xffff0000, v68
	v_lshlrev_b32_e32 v26, 16, v69
	v_and_b32_e32 v27, 0xffff0000, v69
	v_fma_f32 v4, v4, v103, v20
	v_fma_f32 v5, v5, v103, v21
	v_fma_f32 v6, v6, v103, v22
	v_fma_f32 v7, v7, v103, v23
	v_fma_f32 v8, v8, v103, v24
	v_fma_f32 v9, v9, v103, v25
	v_fma_f32 v10, v10, v103, v26
	v_fma_f32 v11, v11, v103, v27
	global_load_dwordx4 v[66:69], v1, s[70:71]
	s_add_u32 s70, s70, 0x200000
	s_addc_u32 s71, s71, 0
	global_load_dword v103, v2, s[100:101]
	s_add_u32 s100, s100, 0x400
	s_addc_u32 s101, s101, 0
	s_waitcnt vmcnt(45)
	v_cvt_pk_bf16_f32 v12, v4, v5
	v_cvt_pk_bf16_f32 v13, v6, v7
	v_cvt_pk_bf16_f32 v14, v8, v9
	v_cvt_pk_bf16_f32 v15, v10, v11
	global_store_dwordx4 v1, v[12:15], s[72:73]
	s_add_u32 s72, s72, 0x200000
	s_addc_u32 s73, s73, 0
	v_lshlrev_b32_e32 v20, 16, v70
	v_and_b32_e32 v21, 0xffff0000, v70
	v_lshlrev_b32_e32 v22, 16, v71
	v_and_b32_e32 v23, 0xffff0000, v71
	v_lshlrev_b32_e32 v24, 16, v72
	v_and_b32_e32 v25, 0xffff0000, v72
	v_lshlrev_b32_e32 v26, 16, v73
	v_and_b32_e32 v27, 0xffff0000, v73
	v_fma_f32 v4, v4, v104, v20
	v_fma_f32 v5, v5, v104, v21
	v_fma_f32 v6, v6, v104, v22
	v_fma_f32 v7, v7, v104, v23
	v_fma_f32 v8, v8, v104, v24
	v_fma_f32 v9, v9, v104, v25
	v_fma_f32 v10, v10, v104, v26
	v_fma_f32 v11, v11, v104, v27
	global_load_dwordx4 v[70:73], v1, s[70:71]
	s_add_u32 s70, s70, 0x200000
	s_addc_u32 s71, s71, 0
	global_load_dword v104, v2, s[100:101]
	s_add_u32 s100, s100, 0x400
	s_addc_u32 s101, s101, 0
	s_waitcnt vmcnt(45)
	v_cvt_pk_bf16_f32 v16, v4, v5
	v_cvt_pk_bf16_f32 v17, v6, v7
	v_cvt_pk_bf16_f32 v18, v8, v9
	v_cvt_pk_bf16_f32 v19, v10, v11
	global_store_dwordx4 v1, v[16:19], s[72:73]
	s_add_u32 s72, s72, 0x200000
	s_addc_u32 s73, s73, 0
	v_lshlrev_b32_e32 v20, 16, v74
	v_and_b32_e32 v21, 0xffff0000, v74
	v_lshlrev_b32_e32 v22, 16, v75
	v_and_b32_e32 v23, 0xffff0000, v75
	v_lshlrev_b32_e32 v24, 16, v76
	v_and_b32_e32 v25, 0xffff0000, v76
	v_lshlrev_b32_e32 v26, 16, v77
	v_and_b32_e32 v27, 0xffff0000, v77
	v_fma_f32 v4, v4, v105, v20
	v_fma_f32 v5, v5, v105, v21
	v_fma_f32 v6, v6, v105, v22
	v_fma_f32 v7, v7, v105, v23
	v_fma_f32 v8, v8, v105, v24
	v_fma_f32 v9, v9, v105, v25
	v_fma_f32 v10, v10, v105, v26
	v_fma_f32 v11, v11, v105, v27
	global_load_dwordx4 v[74:77], v1, s[70:71]
	s_add_u32 s70, s70, 0x200000
	s_addc_u32 s71, s71, 0
	global_load_dword v105, v2, s[100:101]
	s_add_u32 s100, s100, 0x400
	s_addc_u32 s101, s101, 0
	s_waitcnt vmcnt(45)
; __device__ __forceinline__ unsigned pk2(float lo, float hi) { const f32x2_t_ v = {lo, hi}; return __builtin_bit_cast(unsigned, __builtin_convertvector(v, bf16x2_t_)); }
; __device__ __forceinline__ void ssd_s2_phase(Frame& F, bf16* states, const float* decay) {
;     ...
;         for (int c = 0; c < 64; ++c) { const v4u q = sp[(size_t)c * (128 * 64 * 16)]; const float dec = decay[(c * 8 + (h >> 4)) * 32 + (h & 15)];
;             v4u o; o.x = pk2(H[0], H[1]); o.y = pk2(H[2], H[3]); o.z = pk2(H[4], H[5]); o.w = pk2(H[6], H[7]);
;             sp[(size_t)c * (128 * 64 * 16)] = o;
;             H[0] = H[0] * dec + bflo(q.x); H[1] = H[1] * dec + bfhi(q.x); H[2] = H[2] * dec + bflo(q.y); H[3] = H[3] * dec + bfhi(q.y);
;             H[4] = H[4] * dec + bflo(q.z); H[5] = H[5] * dec + bfhi(q.z); H[6] = H[6] * dec + bflo(q.w); H[7] = H[7] * dec + bfhi(q.w); }
	v_cvt_pk_bf16_f32 v12, v4, v5
	v_cvt_pk_bf16_f32 v13, v6, v7
	v_cvt_pk_bf16_f32 v14, v8, v9
	v_cvt_pk_bf16_f32 v15, v10, v11
	global_store_dwordx4 v1, v[12:15], s[72:73]
	s_add_u32 s72, s72, 0x200000
	s_addc_u32 s73, s73, 0
	v_lshlrev_b32_e32 v20, 16, v78
	v_and_b32_e32 v21, 0xffff0000, v78
	v_lshlrev_b32_e32 v22, 16, v79
	v_and_b32_e32 v23, 0xffff0000, v79
	v_lshlrev_b32_e32 v24, 16, v80
	v_and_b32_e32 v25, 0xffff0000, v80
	v_lshlrev_b32_e32 v26, 16, v81
	v_and_b32_e32 v27, 0xffff0000, v81
	v_fma_f32 v4, v4, v106, v20
	v_fma_f32 v5, v5, v106, v21
	v_fma_f32 v6, v6, v106, v22
	v_fma_f32 v7, v7, v106, v23
	v_fma_f32 v8, v8, v106, v24
	v_fma_f32 v9, v9, v106, v25
	v_fma_f32 v10, v10, v106, v26
	v_fma_f32 v11, v11, v106, v27
	global_load_dwordx4 v[78:81], v1, s[70:71]
	s_add_u32 s70, s70, 0x200000
	s_addc_u32 s71, s71, 0
	global_load_dword v106, v2, s[100:101]
	s_add_u32 s100, s100, 0x400
	s_addc_u32 s101, s101, 0
	s_waitcnt vmcnt(45)
	v_cvt_pk_bf16_f32 v16, v4, v5
	v_cvt_pk_bf16_f32 v17, v6, v7
	v_cvt_pk_bf16_f32 v18, v8, v9
	v_cvt_pk_bf16_f32 v19, v10, v11
	global_store_dwordx4 v1, v[16:19], s[72:73]
	s_add_u32 s72, s72, 0x200000
	s_addc_u32 s73, s73, 0
	v_lshlrev_b32_e32 v20, 16, v82
	v_and_b32_e32 v21, 0xffff0000, v82
	v_lshlrev_b32_e32 v22, 16, v83
	v_and_b32_e32 v23, 0xffff0000, v83
	v_lshlrev_b32_e32 v24, 16, v84
	v_and_b32_e32 v25, 0xffff0000, v84
	v_lshlrev_b32_e32 v26, 16, v85
	v_and_b32_e32 v27, 0xffff0000, v85
	v_fma_f32 v4, v4, v107, v20
	v_fma_f32 v5, v5, v107, v21
	v_fma_f32 v6, v6, v107, v22
	v_fma_f32 v7, v7, v107, v23
	v_fma_f32 v8, v8, v107, v24
	v_fma_f32 v9, v9, v107, v25
	v_fma_f32 v10, v10, v107, v26
	v_fma_f32 v11, v11, v107, v27
	global_load_dwordx4 v[82:85], v1, s[70:71]
	s_add_u32 s70, s70, 0x200000
	s_addc_u32 s71, s71, 0
	global_load_dword v107, v2, s[100:101]
	s_add_u32 s100, s100, 0x400
	s_addc_u32 s101, s101, 0
	s_waitcnt vmcnt(45)
	v_cvt_pk_bf16_f32 v12, v4, v5
	v_cvt_pk_bf16_f32 v13, v6, v7
	v_cvt_pk_bf16_f32 v14, v8, v9
	v_cvt_pk_bf16_f32 v15, v10, v11
	global_store_dwordx4 v1, v[12:15], s[72:73]
	s_add_u32 s72, s72, 0x200000
	s_addc_u32 s73, s73, 0
	v_lshlrev_b32_e32 v20, 16, v86
	v_and_b32_e32 v21, 0xffff0000, v86
	v_lshlrev_b32_e32 v22, 16, v87
	v_and_b32_e32 v23, 0xffff0000, v87
	v_lshlrev_b32_e32 v24, 16, v88
	v_and_b32_e32 v25, 0xffff0000, v88
	v_lshlrev_b32_e32 v26, 16, v89
	v_and_b32_e32 v27, 0xffff0000, v89
	v_fma_f32 v4, v4, v108, v20
	v_fma_f32 v5, v5, v108, v21
	v_fma_f32 v6, v6, v108, v22
	v_fma_f32 v7, v7, v108, v23
	v_fma_f32 v8, v8, v108, v24
	v_fma_f32 v9, v9, v108, v25
	v_fma_f32 v10, v10, v108, v26
	v_fma_f32 v11, v11, v108, v27
	global_load_dwordx4 v[86:89], v1, s[70:71]
	s_add_u32 s70, s70, 0x200000
	s_addc_u32 s71, s71, 0
	global_load_dword v108, v2, s[100:101]
	s_add_u32 s100, s100, 0x400
	s_addc_u32 s101, s101, 0
	s_waitcnt vmcnt(45)
	v_cvt_pk_bf16_f32 v16, v4, v5
	v_cvt_pk_bf16_f32 v17, v6, v7
	v_cvt_pk_bf16_f32 v18, v8, v9
	v_cvt_pk_bf16_f32 v19, v10, v11
	global_store_dwordx4 v1, v[16:19], s[72:73]
	s_add_u32 s72, s72, 0x200000
	s_addc_u32 s73, s73, 0
	v_lshlrev_b32_e32 v20, 16, v90
	v_and_b32_e32 v21, 0xffff0000, v90
	v_lshlrev_b32_e32 v22, 16, v91
	v_and_b32_e32 v23, 0xffff0000, v91
	v_lshlrev_b32_e32 v24, 16, v92
	v_and_b32_e32 v25, 0xffff0000, v92
	v_lshlrev_b32_e32 v26, 16, v93
	v_and_b32_e32 v27, 0xffff0000, v93
	v_fma_f32 v4, v4, v109, v20
	v_fma_f32 v5, v5, v109, v21
	v_fma_f32 v6, v6, v109, v22
	v_fma_f32 v7, v7, v109, v23
	v_fma_f32 v8, v8, v109, v24
	v_fma_f32 v9, v9, v109, v25
	v_fma_f32 v10, v10, v109, v26
	v_fma_f32 v11, v11, v109, v27
	global_load_dwordx4 v[90:93], v1, s[70:71]
	s_add_u32 s70, s70, 0x200000
	s_addc_u32 s71, s71, 0
	global_load_dword v109, v2, s[100:101]
	s_add_u32 s100, s100, 0x400
	s_addc_u32 s101, s101, 0
	s_waitcnt vmcnt(45)
	v_cvt_pk_bf16_f32 v12, v4, v5
	v_cvt_pk_bf16_f32 v13, v6, v7
	v_cvt_pk_bf16_f32 v14, v8, v9
	v_cvt_pk_bf16_f32 v15, v10, v11
	global_store_dwordx4 v1, v[12:15], s[72:73]
	s_add_u32 s72, s72, 0x200000
	s_addc_u32 s73, s73, 0
	v_lshlrev_b32_e32 v20, 16, v30
	v_and_b32_e32 v21, 0xffff0000, v30
	v_lshlrev_b32_e32 v22, 16, v31
	v_and_b32_e32 v23, 0xffff0000, v31
	v_lshlrev_b32_e32 v24, 16, v32
	v_and_b32_e32 v25, 0xffff0000, v32
	v_lshlrev_b32_e32 v26, 16, v33
	v_and_b32_e32 v27, 0xffff0000, v33
	v_fma_f32 v4, v4, v94, v20
	v_fma_f32 v5, v5, v94, v21
	v_fma_f32 v6, v6, v94, v22
	v_fma_f32 v7, v7, v94, v23
	v_fma_f32 v8, v8, v94, v24
	v_fma_f32 v9, v9, v94, v25
	v_fma_f32 v10, v10, v94, v26
	v_fma_f32 v11, v11, v94, v27
	s_waitcnt vmcnt(43)
	v_cvt_pk_bf16_f32 v16, v4, v5
	v_cvt_pk_bf16_f32 v17, v6, v7
	v_cvt_pk_bf16_f32 v18, v8, v9
	v_cvt_pk_bf16_f32 v19, v10, v11
	global_store_dwordx4 v1, v[16:19], s[72:73]
	s_add_u32 s72, s72, 0x200000
	s_addc_u32 s73, s73, 0
	v_lshlrev_b32_e32 v20, 16, v34
	v_and_b32_e32 v21, 0xffff0000, v34
	v_lshlrev_b32_e32 v22, 16, v35
	v_and_b32_e32 v23, 0xffff0000, v35
	v_lshlrev_b32_e32 v24, 16, v36
	v_and_b32_e32 v25, 0xffff0000, v36
	v_lshlrev_b32_e32 v26, 16, v37
	v_and_b32_e32 v27, 0xffff0000, v37
	v_fma_f32 v4, v4, v95, v20
	v_fma_f32 v5, v5, v95, v21
	v_fma_f32 v6, v6, v95, v22
	v_fma_f32 v7, v7, v95, v23
	v_fma_f32 v8, v8, v95, v24
	v_fma_f32 v9, v9, v95, v25
	v_fma_f32 v10, v10, v95, v26
	v_fma_f32 v11, v11, v95, v27
	s_waitcnt vmcnt(41)
; __device__ __forceinline__ unsigned pk2(float lo, float hi) { const f32x2_t_ v = {lo, hi}; return __builtin_bit_cast(unsigned, __builtin_convertvector(v, bf16x2_t_)); }
; __device__ __forceinline__ void ssd_s2_phase(Frame& F, bf16* states, const float* decay) {
;     ...
;         for (int c = 0; c < 64; ++c) { const v4u q = sp[(size_t)c * (128 * 64 * 16)]; const float dec = decay[(c * 8 + (h >> 4)) * 32 + (h & 15)];
;             v4u o; o.x = pk2(H[0], H[1]); o.y = pk2(H[2], H[3]); o.z = pk2(H[4], H[5]); o.w = pk2(H[6], H[7]);
;             sp[(size_t)c * (128 * 64 * 16)] = o;
;             H[0] = H[0] * dec + bflo(q.x); H[1] = H[1] * dec + bfhi(q.x); H[2] = H[2] * dec + bflo(q.y); H[3] = H[3] * dec + bfhi(q.y);
;             H[4] = H[4] * dec + bflo(q.z); H[5] = H[5] * dec + bfhi(q.z); H[6] = H[6] * dec + bflo(q.w); H[7] = H[7] * dec + bfhi(q.w); }
	v_cvt_pk_bf16_f32 v12, v4, v5
	v_cvt_pk_bf16_f32 v13, v6, v7
	v_cvt_pk_bf16_f32 v14, v8, v9
	v_cvt_pk_bf16_f32 v15, v10, v11
	global_store_dwordx4 v1, v[12:15], s[72:73]
	s_add_u32 s72, s72, 0x200000
	s_addc_u32 s73, s73, 0
	v_lshlrev_b32_e32 v20, 16, v38
	v_and_b32_e32 v21, 0xffff0000, v38
	v_lshlrev_b32_e32 v22, 16, v39
	v_and_b32_e32 v23, 0xffff0000, v39
	v_lshlrev_b32_e32 v24, 16, v40
	v_and_b32_e32 v25, 0xffff0000, v40
	v_lshlrev_b32_e32 v26, 16, v41
	v_and_b32_e32 v27, 0xffff0000, v41
	v_fma_f32 v4, v4, v96, v20
	v_fma_f32 v5, v5, v96, v21
	v_fma_f32 v6, v6, v96, v22
	v_fma_f32 v7, v7, v96, v23
	v_fma_f32 v8, v8, v96, v24
	v_fma_f32 v9, v9, v96, v25
	v_fma_f32 v10, v10, v96, v26
	v_fma_f32 v11, v11, v96, v27
	s_waitcnt vmcnt(39)
	v_cvt_pk_bf16_f32 v16, v4, v5
	v_cvt_pk_bf16_f32 v17, v6, v7
	v_cvt_pk_bf16_f32 v18, v8, v9
	v_cvt_pk_bf16_f32 v19, v10, v11
	global_store_dwordx4 v1, v[16:19], s[72:73]
	s_add_u32 s72, s72, 0x200000
	s_addc_u32 s73, s73, 0
	v_lshlrev_b32_e32 v20, 16, v42
	v_and_b32_e32 v21, 0xffff0000, v42
	v_lshlrev_b32_e32 v22, 16, v43
	v_and_b32_e32 v23, 0xffff0000, v43
	v_lshlrev_b32_e32 v24, 16, v44
	v_and_b32_e32 v25, 0xffff0000, v44
	v_lshlrev_b32_e32 v26, 16, v45
	v_and_b32_e32 v27, 0xffff0000, v45
	v_fma_f32 v4, v4, v97, v20
	v_fma_f32 v5, v5, v97, v21
	v_fma_f32 v6, v6, v97, v22
	v_fma_f32 v7, v7, v97, v23
	v_fma_f32 v8, v8, v97, v24
	v_fma_f32 v9, v9, v97, v25
	v_fma_f32 v10, v10, v97, v26
	v_fma_f32 v11, v11, v97, v27
	s_waitcnt vmcnt(37)
	v_cvt_pk_bf16_f32 v12, v4, v5
	v_cvt_pk_bf16_f32 v13, v6, v7
	v_cvt_pk_bf16_f32 v14, v8, v9
	v_cvt_pk_bf16_f32 v15, v10, v11
	global_store_dwordx4 v1, v[12:15], s[72:73]
	s_add_u32 s72, s72, 0x200000
	s_addc_u32 s73, s73, 0
	v_lshlrev_b32_e32 v20, 16, v46
	v_and_b32_e32 v21, 0xffff0000, v46
	v_lshlrev_b32_e32 v22, 16, v47
	v_and_b32_e32 v23, 0xffff0000, v47
	v_lshlrev_b32_e32 v24, 16, v48
	v_and_b32_e32 v25, 0xffff0000, v48
	v_lshlrev_b32_e32 v26, 16, v49
	v_and_b32_e32 v27, 0xffff0000, v49
	v_fma_f32 v4, v4, v98, v20
	v_fma_f32 v5, v5, v98, v21
	v_fma_f32 v6, v6, v98, v22
	v_fma_f32 v7, v7, v98, v23
	v_fma_f32 v8, v8, v98, v24
	v_fma_f32 v9, v9, v98, v25
	v_fma_f32 v10, v10, v98, v26
	v_fma_f32 v11, v11, v98, v27
	s_waitcnt vmcnt(35)
	v_cvt_pk_bf16_f32 v16, v4, v5
	v_cvt_pk_bf16_f32 v17, v6, v7
	v_cvt_pk_bf16_f32 v18, v8, v9
	v_cvt_pk_bf16_f32 v19, v10, v11
	global_store_dwordx4 v1, v[16:19], s[72:73]
	s_add_u32 s72, s72, 0x200000
	s_addc_u32 s73, s73, 0
	v_lshlrev_b32_e32 v20, 16, v50
	v_and_b32_e32 v21, 0xffff0000, v50
	v_lshlrev_b32_e32 v22, 16, v51
	v_and_b32_e32 v23, 0xffff0000, v51
	v_lshlrev_b32_e32 v24, 16, v52
	v_and_b32_e32 v25, 0xffff0000, v52
	v_lshlrev_b32_e32 v26, 16, v53
	v_and_b32_e32 v27, 0xffff0000, v53
	v_fma_f32 v4, v4, v99, v20
	v_fma_f32 v5, v5, v99, v21
	v_fma_f32 v6, v6, v99, v22
	v_fma_f32 v7, v7, v99, v23
	v_fma_f32 v8, v8, v99, v24
	v_fma_f32 v9, v9, v99, v25
	v_fma_f32 v10, v10, v99, v26
	v_fma_f32 v11, v11, v99, v27
	s_waitcnt vmcnt(33)
	v_cvt_pk_bf16_f32 v12, v4, v5
	v_cvt_pk_bf16_f32 v13, v6, v7
	v_cvt_pk_bf16_f32 v14, v8, v9
	v_cvt_pk_bf16_f32 v15, v10, v11
	global_store_dwordx4 v1, v[12:15], s[72:73]
	s_add_u32 s72, s72, 0x200000
	s_addc_u32 s73, s73, 0
	v_lshlrev_b32_e32 v20, 16, v54
	v_and_b32_e32 v21, 0xffff0000, v54
	v_lshlrev_b32_e32 v22, 16, v55
	v_and_b32_e32 v23, 0xffff0000, v55
	v_lshlrev_b32_e32 v24, 16, v56
	v_and_b32_e32 v25, 0xffff0000, v56
	v_lshlrev_b32_e32 v26, 16, v57
	v_and_b32_e32 v27, 0xffff0000, v57
	v_fma_f32 v4, v4, v100, v20
	v_fma_f32 v5, v5, v100, v21
	v_fma_f32 v6, v6, v100, v22
	v_fma_f32 v7, v7, v100, v23
	v_fma_f32 v8, v8, v100, v24
	v_fma_f32 v9, v9, v100, v25
	v_fma_f32 v10, v10, v100, v26
	v_fma_f32 v11, v11, v100, v27
	s_waitcnt vmcnt(31)
	v_cvt_pk_bf16_f32 v16, v4, v5
	v_cvt_pk_bf16_f32 v17, v6, v7
	v_cvt_pk_bf16_f32 v18, v8, v9
	v_cvt_pk_bf16_f32 v19, v10, v11
	global_store_dwordx4 v1, v[16:19], s[72:73]
	s_add_u32 s72, s72, 0x200000
	s_addc_u32 s73, s73, 0
	v_lshlrev_b32_e32 v20, 16, v58
	v_and_b32_e32 v21, 0xffff0000, v58
	v_lshlrev_b32_e32 v22, 16, v59
	v_and_b32_e32 v23, 0xffff0000, v59
	v_lshlrev_b32_e32 v24, 16, v60
	v_and_b32_e32 v25, 0xffff0000, v60
	v_lshlrev_b32_e32 v26, 16, v61
	v_and_b32_e32 v27, 0xffff0000, v61
	v_fma_f32 v4, v4, v101, v20
	v_fma_f32 v5, v5, v101, v21
	v_fma_f32 v6, v6, v101, v22
	v_fma_f32 v7, v7, v101, v23
	v_fma_f32 v8, v8, v101, v24
	v_fma_f32 v9, v9, v101, v25
	v_fma_f32 v10, v10, v101, v26
	v_fma_f32 v11, v11, v101, v27
	s_waitcnt vmcnt(29)
	v_cvt_pk_bf16_f32 v12, v4, v5
	v_cvt_pk_bf16_f32 v13, v6, v7
	v_cvt_pk_bf16_f32 v14, v8, v9
	v_cvt_pk_bf16_f32 v15, v10, v11
	global_store_dwordx4 v1, v[12:15], s[72:73]
	s_add_u32 s72, s72, 0x200000
	s_addc_u32 s73, s73, 0
	v_lshlrev_b32_e32 v20, 16, v62
	v_and_b32_e32 v21, 0xffff0000, v62
	v_lshlrev_b32_e32 v22, 16, v63
	v_and_b32_e32 v23, 0xffff0000, v63
	v_lshlrev_b32_e32 v24, 16, v64
	v_and_b32_e32 v25, 0xffff0000, v64
	v_lshlrev_b32_e32 v26, 16, v65
	v_and_b32_e32 v27, 0xffff0000, v65
	v_fma_f32 v4, v4, v102, v20
	v_fma_f32 v5, v5, v102, v21
	v_fma_f32 v6, v6, v102, v22
	v_fma_f32 v7, v7, v102, v23
	v_fma_f32 v8, v8, v102, v24
	v_fma_f32 v9, v9, v102, v25
	v_fma_f32 v10, v10, v102, v26
	v_fma_f32 v11, v11, v102, v27
	s_waitcnt vmcnt(27)
	v_cvt_pk_bf16_f32 v16, v4, v5
	v_cvt_pk_bf16_f32 v17, v6, v7
	v_cvt_pk_bf16_f32 v18, v8, v9
	v_cvt_pk_bf16_f32 v19, v10, v11
	global_store_dwordx4 v1, v[16:19], s[72:73]
	s_add_u32 s72, s72, 0x200000
	s_addc_u32 s73, s73, 0
	v_lshlrev_b32_e32 v20, 16, v66
	v_and_b32_e32 v21, 0xffff0000, v66
	v_lshlrev_b32_e32 v22, 16, v67
	v_and_b32_e32 v23, 0xffff0000, v67
	v_lshlrev_b32_e32 v24, 16, v68
	v_and_b32_e32 v25, 0xffff0000, v68
	v_lshlrev_b32_e32 v26, 16, v69
	v_and_b32_e32 v27, 0xffff0000, v69
	v_fma_f32 v4, v4, v103, v20
	v_fma_f32 v5, v5, v103, v21
	v_fma_f32 v6, v6, v103, v22
	v_fma_f32 v7, v7, v103, v23
	v_fma_f32 v8, v8, v103, v24
	v_fma_f32 v9, v9, v103, v25
	v_fma_f32 v10, v10, v103, v26
	v_fma_f32 v11, v11, v103, v27
	s_waitcnt vmcnt(25)
; __device__ __forceinline__ unsigned pk2(float lo, float hi) { const f32x2_t_ v = {lo, hi}; return __builtin_bit_cast(unsigned, __builtin_convertvector(v, bf16x2_t_)); }
; __device__ __forceinline__ void xcd_barrier(const XcdBarrier& b) {
;     asm volatile("s_waitcnt vmcnt(0)" ::: "memory");
;     __syncthreads();
;     if (threadIdx.x == 0) {
;         unsigned* bar = b.bar;
;         __builtin_amdgcn_s_waitcnt(0);
;         unsigned nloc = b.st[0], nx = b.st[1];
;         if (nloc == 0u) { xcd_barrier_complete(bar, b.x, nloc, nx); b.st[0] = nloc; b.st[1] = nx; }
; __device__ __forceinline__ void ssd_s2_phase(Frame& F, bf16* states, const float* decay) {
;     ...
;         for (int c = 0; c < 64; ++c) { const v4u q = sp[(size_t)c * (128 * 64 * 16)]; const float dec = decay[(c * 8 + (h >> 4)) * 32 + (h & 15)];
;             v4u o; o.x = pk2(H[0], H[1]); o.y = pk2(H[2], H[3]); o.z = pk2(H[4], H[5]); o.w = pk2(H[6], H[7]);
;             sp[(size_t)c * (128 * 64 * 16)] = o;
;             H[0] = H[0] * dec + bflo(q.x); H[1] = H[1] * dec + bfhi(q.x); H[2] = H[2] * dec + bflo(q.y); H[3] = H[3] * dec + bfhi(q.y);
;             H[4] = H[4] * dec + bflo(q.z); H[5] = H[5] * dec + bfhi(q.z); H[6] = H[6] * dec + bflo(q.w); H[7] = H[7] * dec + bfhi(q.w); }
	v_cvt_pk_bf16_f32 v12, v4, v5
	v_cvt_pk_bf16_f32 v13, v6, v7
	v_cvt_pk_bf16_f32 v14, v8, v9
	v_cvt_pk_bf16_f32 v15, v10, v11
	global_store_dwordx4 v1, v[12:15], s[72:73]
	s_add_u32 s72, s72, 0x200000
	s_addc_u32 s73, s73, 0
	v_lshlrev_b32_e32 v20, 16, v70
	v_and_b32_e32 v21, 0xffff0000, v70
	v_lshlrev_b32_e32 v22, 16, v71
	v_and_b32_e32 v23, 0xffff0000, v71
	v_lshlrev_b32_e32 v24, 16, v72
	v_and_b32_e32 v25, 0xffff0000, v72
	v_lshlrev_b32_e32 v26, 16, v73
	v_and_b32_e32 v27, 0xffff0000, v73
	v_fma_f32 v4, v4, v104, v20
	v_fma_f32 v5, v5, v104, v21
	v_fma_f32 v6, v6, v104, v22
	v_fma_f32 v7, v7, v104, v23
	v_fma_f32 v8, v8, v104, v24
	v_fma_f32 v9, v9, v104, v25
	v_fma_f32 v10, v10, v104, v26
	v_fma_f32 v11, v11, v104, v27
	s_waitcnt vmcnt(23)
	v_cvt_pk_bf16_f32 v16, v4, v5
	v_cvt_pk_bf16_f32 v17, v6, v7
	v_cvt_pk_bf16_f32 v18, v8, v9
	v_cvt_pk_bf16_f32 v19, v10, v11
	global_store_dwordx4 v1, v[16:19], s[72:73]
	s_add_u32 s72, s72, 0x200000
	s_addc_u32 s73, s73, 0
	v_lshlrev_b32_e32 v20, 16, v74
	v_and_b32_e32 v21, 0xffff0000, v74
	v_lshlrev_b32_e32 v22, 16, v75
	v_and_b32_e32 v23, 0xffff0000, v75
	v_lshlrev_b32_e32 v24, 16, v76
	v_and_b32_e32 v25, 0xffff0000, v76
	v_lshlrev_b32_e32 v26, 16, v77
	v_and_b32_e32 v27, 0xffff0000, v77
	v_fma_f32 v4, v4, v105, v20
	v_fma_f32 v5, v5, v105, v21
	v_fma_f32 v6, v6, v105, v22
	v_fma_f32 v7, v7, v105, v23
	v_fma_f32 v8, v8, v105, v24
	v_fma_f32 v9, v9, v105, v25
	v_fma_f32 v10, v10, v105, v26
	v_fma_f32 v11, v11, v105, v27
	s_waitcnt vmcnt(21)
	v_cvt_pk_bf16_f32 v12, v4, v5
	v_cvt_pk_bf16_f32 v13, v6, v7
	v_cvt_pk_bf16_f32 v14, v8, v9
	v_cvt_pk_bf16_f32 v15, v10, v11
	global_store_dwordx4 v1, v[12:15], s[72:73]
	s_add_u32 s72, s72, 0x200000
	s_addc_u32 s73, s73, 0
	v_lshlrev_b32_e32 v20, 16, v78
	v_and_b32_e32 v21, 0xffff0000, v78
	v_lshlrev_b32_e32 v22, 16, v79
	v_and_b32_e32 v23, 0xffff0000, v79
	v_lshlrev_b32_e32 v24, 16, v80
	v_and_b32_e32 v25, 0xffff0000, v80
	v_lshlrev_b32_e32 v26, 16, v81
	v_and_b32_e32 v27, 0xffff0000, v81
	v_fma_f32 v4, v4, v106, v20
	v_fma_f32 v5, v5, v106, v21
	v_fma_f32 v6, v6, v106, v22
	v_fma_f32 v7, v7, v106, v23
	v_fma_f32 v8, v8, v106, v24
	v_fma_f32 v9, v9, v106, v25
	v_fma_f32 v10, v10, v106, v26
	v_fma_f32 v11, v11, v106, v27
	s_waitcnt vmcnt(19)
	v_cvt_pk_bf16_f32 v16, v4, v5
	v_cvt_pk_bf16_f32 v17, v6, v7
	v_cvt_pk_bf16_f32 v18, v8, v9
	v_cvt_pk_bf16_f32 v19, v10, v11
	global_store_dwordx4 v1, v[16:19], s[72:73]
	s_add_u32 s72, s72, 0x200000
	s_addc_u32 s73, s73, 0
	v_lshlrev_b32_e32 v20, 16, v82
	v_and_b32_e32 v21, 0xffff0000, v82
	v_lshlrev_b32_e32 v22, 16, v83
	v_and_b32_e32 v23, 0xffff0000, v83
	v_lshlrev_b32_e32 v24, 16, v84
	v_and_b32_e32 v25, 0xffff0000, v84
	v_lshlrev_b32_e32 v26, 16, v85
	v_and_b32_e32 v27, 0xffff0000, v85
	v_fma_f32 v4, v4, v107, v20
	v_fma_f32 v5, v5, v107, v21
	v_fma_f32 v6, v6, v107, v22
	v_fma_f32 v7, v7, v107, v23
	v_fma_f32 v8, v8, v107, v24
	v_fma_f32 v9, v9, v107, v25
	v_fma_f32 v10, v10, v107, v26
	v_fma_f32 v11, v11, v107, v27
	s_waitcnt vmcnt(17)
	v_cvt_pk_bf16_f32 v12, v4, v5
	v_cvt_pk_bf16_f32 v13, v6, v7
	v_cvt_pk_bf16_f32 v14, v8, v9
	v_cvt_pk_bf16_f32 v15, v10, v11
	global_store_dwordx4 v1, v[12:15], s[72:73]
	s_add_u32 s72, s72, 0x200000
	s_addc_u32 s73, s73, 0
	v_lshlrev_b32_e32 v20, 16, v86
	v_and_b32_e32 v21, 0xffff0000, v86
	v_lshlrev_b32_e32 v22, 16, v87
	v_and_b32_e32 v23, 0xffff0000, v87
	v_lshlrev_b32_e32 v24, 16, v88
	v_and_b32_e32 v25, 0xffff0000, v88
	v_lshlrev_b32_e32 v26, 16, v89
	v_and_b32_e32 v27, 0xffff0000, v89
	v_fma_f32 v4, v4, v108, v20
	v_fma_f32 v5, v5, v108, v21
	v_fma_f32 v6, v6, v108, v22
	v_fma_f32 v7, v7, v108, v23
	v_fma_f32 v8, v8, v108, v24
	v_fma_f32 v9, v9, v108, v25
	v_fma_f32 v10, v10, v108, v26
	v_fma_f32 v11, v11, v108, v27
	s_waitcnt vmcnt(15)
	v_cvt_pk_bf16_f32 v16, v4, v5
	v_cvt_pk_bf16_f32 v17, v6, v7
	v_cvt_pk_bf16_f32 v18, v8, v9
	v_cvt_pk_bf16_f32 v19, v10, v11
	global_store_dwordx4 v1, v[16:19], s[72:73]
	s_add_u32 s72, s72, 0x200000
	s_addc_u32 s73, s73, 0
	v_lshlrev_b32_e32 v20, 16, v90
	v_and_b32_e32 v21, 0xffff0000, v90
	v_lshlrev_b32_e32 v22, 16, v91
	v_and_b32_e32 v23, 0xffff0000, v91
	v_lshlrev_b32_e32 v24, 16, v92
	v_and_b32_e32 v25, 0xffff0000, v92
	v_lshlrev_b32_e32 v26, 16, v93
	v_and_b32_e32 v27, 0xffff0000, v93
	v_fma_f32 v4, v4, v109, v20
	v_fma_f32 v5, v5, v109, v21
	v_fma_f32 v6, v6, v109, v22
	v_fma_f32 v7, v7, v109, v23
	v_fma_f32 v8, v8, v109, v24
	v_fma_f32 v9, v9, v109, v25
	v_fma_f32 v10, v10, v109, v26
	v_fma_f32 v11, v11, v109, v27
	s_add_u32 s98, s98, s99
	s_branch .Ls2a_outer
.Ls2a_done:
.LBB0_494:
	s_load_dwordx2 s[0:1], s[74:75], 0x100
	s_waitcnt lgkmcnt(0)
	s_cmp_gt_i32 s1, 5
	s_cselect_b64 s[0:1], -1, 0
	s_and_b64 s[2:3], s[2:3], s[0:1]
	s_andn2_b64 vcc, exec, s[2:3]
	s_cbranch_vccnz .LBB0_544
	s_waitcnt vmcnt(0)
	v_cmp_eq_u32_e32 vcc, 0, v0
	s_barrier
	s_and_saveexec_b64 s[2:3], vcc
	s_cbranch_execz .LBB0_543
	v_readlane_b32 s4, v251, 7
	s_waitcnt vmcnt(0) expcnt(0) lgkmcnt(0)
	s_nop 0
	v_mov_b32_e32 v1, s4
	ds_read_b32 v3, v1
	ds_read_b32 v1, v1 offset:4
	s_waitcnt lgkmcnt(1)
	v_cmp_ne_u32_e32 vcc, 0, v3
	s_cbranch_vccnz .LBB0_511
	v_readlane_b32 s4, v251, 2
	v_readlane_b32 s5, v251, 3
	s_load_dwordx2 s[8:9], s[4:5], 0x4
	s_load_dword s10, s[74:75], 0x108
	s_add_u32 s4, s78, 0x4200
	s_addc_u32 s5, s79, 0
	s_add_u32 s6, s78, 0x4400
	s_addc_u32 s7, s79, 0
	s_waitcnt lgkmcnt(0)
	s_mul_i32 s33, s8, s10
	s_add_u32 s8, s78, 0x4500
	s_mul_i32 s33, s33, s9
	s_addc_u32 s9, s79, 0
	s_add_u32 s10, s78, 0x4600
	s_addc_u32 s11, s79, 0
	s_add_u32 s12, s78, 0x4700
	s_addc_u32 s13, s79, 0
	s_add_u32 s14, s78, 0x4800
	s_addc_u32 s15, s79, 0
	s_add_u32 s16, s78, 0x4900
	s_addc_u32 s17, s79, 0
	s_add_u32 s18, s78, 0x4a00
	s_addc_u32 s19, s79, 0
	s_add_u32 s20, s78, 0x4b00
	s_addc_u32 s21, s79, 0
	s_add_u32 s22, s78, 0x4c00
	s_addc_u32 s23, s79, 0
	s_add_u32 s24, s78, 0x4d00
	s_addc_u32 s25, s79, 0
	s_add_u32 s26, s78, 0x4e00
	s_addc_u32 s27, s79, 0
	s_add_u32 s28, s78, 0x4f00
	s_addc_u32 s29, s79, 0
	s_add_u32 s30, s78, 0x5000
	s_addc_u32 s31, s79, 0
	s_add_u32 s34, s78, 0x5100
	s_addc_u32 s35, s79, 0
	s_add_u32 s36, s78, 0x5200
	s_addc_u32 s37, s79, 0
	s_add_u32 s38, s78, 0x5300
	s_addc_u32 s39, s79, 0
	s_mov_b32 s46, 1
	v_mov_b32_e32 v17, 0
	s_branch .LBB0_499

; __device__ __forceinline__ void ssd_s2_phase(Frame& F, bf16* states, const float* decay) {
;     for (int it = blockIdx.x * 512 + F.tid; it < SSD_NH * 64 * 16; it += F.G * 512) {
.LBB0_2194:
	s_load_dwordx2 s[2:3], s[74:75], 0x100
	s_waitcnt lgkmcnt(0)
	s_cmp_lt_i32 s2, 22
	s_cselect_b64 s[2:3], -1, 0
	s_and_b64 s[2:3], s[2:3], s[0:1]
	s_andn2_b64 vcc, exec, s[2:3]
	s_cbranch_vccnz .LBB0_2201
	s_load_dword s99, s[74:75], 0x108
	s_lshl_b32 s98, s93, 9
	s_add_i32 s98, s98, s94
	v_lshlrev_b32_e32 v1, 4, v186
	v_mov_b32_e32 v2, 0
	s_waitcnt lgkmcnt(0)
	s_lshl_b32 s99, s99, 9

; __device__ __forceinline__ unsigned xb_add(unsigned* p, unsigned v) { return __hip_atomic_fetch_add(p, v, __ATOMIC_RELAXED, __HIP_MEMORY_SCOPE_AGENT); }
; __device__ __forceinline__ void xcd_barrier(const XcdBarrier& b) {
;     asm volatile("s_waitcnt vmcnt(0)" ::: "memory");
;     __syncthreads();
;     if (threadIdx.x == 0) {
;         unsigned* bar = b.bar;
;         __builtin_amdgcn_s_waitcnt(0);
;         unsigned nloc = b.st[0], nx = b.st[1];
;         if (nloc == 0u) { xcd_barrier_complete(bar, b.x, nloc, nx); b.st[0] = nloc; b.st[1] = nx; }
;         const unsigned old = xb_add(&bar[XB_XSUB(b.x)], 1u);
.Ls2b_done:
.LBB0_2201:
	s_load_dwordx2 s[0:1], s[74:75], 0x100
	s_waitcnt lgkmcnt(0)
	s_cmp_gt_i32 s1, 22
	s_cselect_b64 s[0:1], -1, 0
	s_and_b64 s[2:3], s[2:3], s[0:1]
	s_andn2_b64 vcc, exec, s[2:3]
	s_cbranch_vccnz .LBB0_2251
	s_waitcnt vmcnt(0)
	v_cmp_eq_u32_e32 vcc, 0, v0
	s_waitcnt vmcnt(0)
	s_barrier
	s_and_saveexec_b64 s[2:3], vcc
	s_cbranch_execz .LBB0_2250
	v_readlane_b32 s4, v251, 7
	s_waitcnt vmcnt(0) expcnt(0) lgkmcnt(0)
	s_nop 0
	v_mov_b32_e32 v1, s4
	ds_read_b32 v3, v1
	ds_read_b32 v1, v1 offset:4
	s_waitcnt lgkmcnt(1)
	v_cmp_ne_u32_e32 vcc, 0, v3
	s_cbranch_vccnz .LBB0_2218
	v_readlane_b32 s4, v251, 2
	v_readlane_b32 s5, v251, 3
	s_load_dwordx2 s[8:9], s[4:5], 0x4
	s_add_u32 s4, s78, 0x4200
	s_addc_u32 s5, s79, 0
	s_add_u32 s6, s78, 0x4400
	s_addc_u32 s7, s79, 0
	v_readlane_b32 s10, v251, 0
	s_waitcnt lgkmcnt(0)
	s_mul_i32 s33, s8, s10
	s_add_u32 s8, s78, 0x4500
	s_mul_i32 s33, s33, s9
	s_addc_u32 s9, s79, 0
	v_readlane_b32 s11, v251, 1
	s_add_u32 s10, s78, 0x4600
	s_addc_u32 s11, s79, 0
	s_add_u32 s12, s78, 0x4700
	s_addc_u32 s13, s79, 0
	s_add_u32 s14, s78, 0x4800
	s_addc_u32 s15, s79, 0
	s_add_u32 s16, s78, 0x4900
	s_addc_u32 s17, s79, 0
	s_add_u32 s18, s78, 0x4a00
	s_addc_u32 s19, s79, 0
	s_add_u32 s20, s78, 0x4b00
	s_addc_u32 s21, s79, 0
	s_add_u32 s22, s78, 0x4c00
	s_addc_u32 s23, s79, 0
	s_add_u32 s24, s78, 0x4d00
	s_addc_u32 s25, s79, 0
	s_add_u32 s26, s78, 0x4e00
	s_addc_u32 s27, s79, 0
	s_add_u32 s28, s78, 0x4f00
	s_addc_u32 s29, s79, 0
	s_add_u32 s30, s78, 0x5000
	s_addc_u32 s31, s79, 0
	s_add_u32 s34, s78, 0x5100
	s_addc_u32 s35, s79, 0
	s_add_u32 s36, s78, 0x5200
	s_addc_u32 s37, s79, 0
	s_add_u32 s38, s78, 0x5300
	s_addc_u32 s39, s79, 0
	s_mov_b32 s46, 1
	v_mov_b32_e32 v17, 0
	s_branch .LBB0_2206

; __global__ void __launch_bounds__(NWAVES * 64, 2) mk_fwd(Args args) {
	.amdhsa_kernel _Z6mk_fwd4Args
		.amdhsa_group_segment_fixed_size 0
		.amdhsa_private_segment_fixed_size 0
		.amdhsa_kernarg_size 520
		.amdhsa_user_sgpr_count 2
		.amdhsa_user_sgpr_dispatch_ptr 0
		.amdhsa_user_sgpr_queue_ptr 0
		.amdhsa_user_sgpr_kernarg_segment_ptr 1
		.amdhsa_user_sgpr_dispatch_id 0
		.amdhsa_user_sgpr_kernarg_preload_length 0
		.amdhsa_user_sgpr_kernarg_preload_offset 0
		.amdhsa_user_sgpr_private_segment_size 0
		.amdhsa_uses_dynamic_stack 0
		.amdhsa_enable_private_segment 0
		.amdhsa_system_sgpr_workgroup_id_x 1
		.amdhsa_system_sgpr_workgroup_id_y 0
		.amdhsa_system_sgpr_workgroup_id_z 0
		.amdhsa_system_sgpr_workgroup_info 0
		.amdhsa_system_vgpr_workitem_id 0
		.amdhsa_next_free_vgpr 253
		.amdhsa_next_free_sgpr 102
		.amdhsa_accum_offset 256
		.amdhsa_reserve_vcc 1
		.amdhsa_float_round_mode_32 0
		.amdhsa_float_round_mode_16_64 0
		.amdhsa_float_denorm_mode_32 3
		.amdhsa_float_denorm_mode_16_64 3
		.amdhsa_dx10_clamp 1
		.amdhsa_ieee_mode 1
		.amdhsa_fp16_overflow 0
		.amdhsa_tg_split 0
		.amdhsa_exception_fp_ieee_invalid_op 0
		.amdhsa_exception_fp_denorm_src 0
		.amdhsa_exception_fp_ieee_div_zero 0
		.amdhsa_exception_fp_ieee_overflow 0
		.amdhsa_exception_fp_ieee_underflow 0
		.amdhsa_exception_fp_ieee_inexact 0
		.amdhsa_exception_int_div_zero 0
	.end_amdhsa_kernel

; __global__ void __launch_bounds__(NWAVES * 64, 2) mk_fwd(Args args) {
amdhsa.kernels:
  - .agpr_count:     0
    .args:
      - .offset:         0
        .size:           264
        .value_kind:     by_value
      - .offset:         264
        .size:           4
        .value_kind:     hidden_block_count_x
      - .offset:         268
        .size:           4
        .value_kind:     hidden_block_count_y
      - .offset:         272
        .size:           4
        .value_kind:     hidden_block_count_z
      - .offset:         276
        .size:           2
        .value_kind:     hidden_group_size_x
      - .offset:         278
        .size:           2
        .value_kind:     hidden_group_size_y
      - .offset:         280
        .size:           2
        .value_kind:     hidden_group_size_z
      - .offset:         282
        .size:           2
        .value_kind:     hidden_remainder_x
      - .offset:         284
        .size:           2
        .value_kind:     hidden_remainder_y
      - .offset:         286
        .size:           2
        .value_kind:     hidden_remainder_z
      - .offset:         304
        .size:           8
        .value_kind:     hidden_global_offset_x
      - .offset:         312
        .size:           8
        .value_kind:     hidden_global_offset_y
      - .offset:         320
        .size:           8
        .value_kind:     hidden_global_offset_z
      - .offset:         328
        .size:           2
        .value_kind:     hidden_grid_dims
      - .offset:         384
        .size:           4
        .value_kind:     hidden_dynamic_lds_size
    .group_segment_fixed_size: 0
    .kernarg_segment_align: 8
    .kernarg_segment_size: 520
    .language:       OpenCL C
    .language_version:
      - 2
      - 0
    .max_flat_workgroup_size: 512
    .name:           _Z6mk_fwd4Args
    .private_segment_fixed_size: 0
    .sgpr_count:     108
    .sgpr_spill_count: 731
    .symbol:         _Z6mk_fwd4Args.kd
    .uniform_work_group_size: 1
    .uses_dynamic_stack: false
    .vgpr_count:     253
    .vgpr_spill_count: 0
    .wavefront_size: 64
